# LRU pass-1: next unit's input rows touched into L2 during the current unit (index broadcast via LDS)
# baseline (speedup 1.0000x reference)
; #define GAS __attribute__((address_space(1)))
; #define LAS __attribute__((address_space(3)))
; template <int PASS>
; __device__ __forceinline__ void lru_unit(const LruPtrs& args, LAS unsigned char* lds, int chunk, int bl, int g, int ck) {
;     ...
;         { const float* src = (w < 4) ? args.conv_w + w * D : (w == 4) ? args.conv_b : (w == 5) ? args.b_lru_r : (w == 6) ? args.b_lru_i : (const float*)(ws + WS_COEF);
;           PRM[w * 64 + lane] = ((const GAS float*)src)[g * 64 + lane]; }
;         LAS bf16* XT = (LAS bf16*)(lds + RING_OFF + 32768 + w * 4864);
;         {
;             const int tl0 = ck * 256 + w * 32;
;             v4u xv[5];
; #pragma unroll
;             for (int i = 0; i < 5; ++i) { const int idx = lane + 64 * i, r = idx >> 3, ch = idx & 7; const int ts = tl0 - 3 + r;
;                 xv[i] = (v4u){0u, 0u, 0u, 0u};
;                 if (r < 35 && ts >= 0) xv[i] = *(const GAS v4u*)(Z + ((size_t)bl * T + ts) * LDZ + ZC_AX + g * 64 + ch * 8); }
; #pragma unroll
;             for (int i = 0; i < 5; ++i) { const int idx = lane + 64 * i, r = idx >> 3, ch = idx & 7;
;                 if (r < 35) { *(LAS v2u*)(XT + r * 68 + ch * 8) = (v2u){xv[i].x, xv[i].y}; *(LAS v2u*)(XT + r * 68 + ch * 8 + 4) = (v2u){xv[i].z, xv[i].w}; } }
;         }
;         __syncthreads();
;         v2u xw[4][8];
; #pragma unroll
;         for (int k = 0; k < 4; ++k)
; #pragma unroll
;             for (int q = 0; q < 8; ++q) xw[k][q] = *(const LAS v2u*)(XT + (n + k) * 68 + 8 * q + 4 * hi);
;         float xc[8][4];
; #pragma unroll
;         for (int q = 0; q < 8; ++q) { const f32x4 bb = *(const LAS f32x4*)(PRM + 4 * 64 + 8 * q + 4 * hi);
; #pragma unroll
;             for (int p = 0; p < 4; ++p) xc[q][p] = bb[p]; }
; #pragma unroll
;         for (int k = 0; k < 4; ++k) {
; #pragma unroll
;             for (int q = 0; q < 8; ++q) { const f32x4 cw = *(const LAS f32x4*)(PRM + k * 64 + 8 * q + 4 * hi);
;                 xc[q][0] += cw[0] * pg8::bf_lo(xw[k][q].x); xc[q][1] += cw[1] * pg8::bf_hi(xw[k][q].x); xc[q][2] += cw[2] * pg8::bf_lo(xw[k][q].y); xc[q][3] += cw[3] * pg8::bf_hi(xw[k][q].y); }
.LBB0_443:
	s_or_b64 exec, exec, s[4:5]
	s_mul_i32 s4, s48, 0x1300
	s_add_i32 s50, s4, 0
	v_lshl_add_u32 v0, v26, 1, s50
	s_movk_i32 s4, 0x88
	v_mad_u32_u24 v22, v25, s4, v0
	v_add_u32_e32 v23, 0x8000, v22
	s_waitcnt vmcnt(0)
	s_and_saveexec_b64 s[100:101], s[10:11]
	v_mov_b32_e32 v180, s86
	ds_write_b32 v180, v252 offset:64
	s_or_b64 exec, exec, s[100:101]
	ds_write_b32 v179, v178 offset:12288
	ds_write2_b64 v23, v[6:7], v[8:9] offset1:1
	v_add_u32_e32 v6, 0x8440, v22
	ds_write2_b64 v6, v[2:3], v[4:5] offset1:1
	v_add_u32_e32 v2, 0x8880, v22
	ds_write2_b64 v2, v[14:15], v[16:17] offset1:1
	v_add_u32_e32 v2, 0x8cc0, v22
	ds_write2_b64 v2, v[10:11], v[12:13] offset1:1
	s_and_saveexec_b64 s[4:5], vcc
	v_mul_u32_u24_e32 v2, 0x88, v27
	v_add3_u32 v0, v0, v2, s79
	ds_write2_b64 v0, v[18:19], v[20:21] offset1:1
	s_or_b64 exec, exec, s[4:5]
	v_lshrrev_b32_e32 v2, 3, v24
	v_and_b32_e32 v87, 31, v24
	v_and_b32_e32 v88, 4, v2
	v_lshlrev_b32_e32 v2, 1, v88
	v_mul_u32_u24_e32 v3, 0x88, v87
	v_add3_u32 v2, s50, v2, v3
	v_add_u32_e32 v10, 0x8000, v2
	v_lshl_add_u32 v89, v88, 2, 0
	s_waitcnt lgkmcnt(0)
	s_barrier
	ds_read2_b64 v[90:93], v10 offset1:2
	ds_read2_b64 v[82:85], v10 offset0:4 offset1:6
	ds_read2_b64 v[50:53], v10 offset0:8 offset1:10
	ds_read2_b64 v[2:5], v10 offset0:12 offset1:14
	ds_read2_b64 v[94:97], v10 offset0:17 offset1:19
	ds_read2_b64 v[98:101], v10 offset0:21 offset1:23
	ds_read2_b64 v[54:57], v10 offset0:25 offset1:27
	ds_read2_b64 v[6:9], v10 offset0:29 offset1:31
	ds_read2_b64 v[34:37], v10 offset0:34 offset1:36
	ds_read2_b64 v[26:29], v10 offset0:38 offset1:40
	ds_read2_b64 v[18:21], v10 offset0:42 offset1:44
	ds_read2_b64 v[66:69], v10 offset0:46 offset1:48
	ds_read2_b64 v[38:41], v10 offset0:51 offset1:53
	ds_read2_b64 v[30:33], v10 offset0:55 offset1:57
	ds_read2_b64 v[22:25], v10 offset0:59 offset1:61
	ds_read2_b64 v[70:73], v10 offset0:63 offset1:65
	ds_read_b128 v[102:105], v89 offset:13312
	ds_read_b128 v[106:109], v89 offset:13344
	ds_read_b128 v[110:113], v89 offset:13376
	ds_read_b128 v[114:117], v89 offset:13408
	ds_read_b128 v[74:77], v89 offset:13440
	ds_read_b128 v[58:61], v89 offset:13472
	ds_read_b128 v[42:45], v89 offset:13504
	ds_read_b128 v[10:13], v89 offset:13536
	ds_read_b128 v[118:121], v89 offset:12288
	ds_read_b128 v[122:125], v89 offset:12320
	ds_read_b128 v[126:129], v89 offset:12352
	ds_read_b128 v[130:133], v89 offset:12384
	ds_read_b128 v[78:81], v89 offset:12416
	ds_read_b128 v[62:65], v89 offset:12448
	ds_read_b128 v[46:49], v89 offset:12480
	ds_read_b128 v[14:17], v89 offset:12512
	ds_read_b128 v[134:137], v89 offset:12544
	s_waitcnt lgkmcnt(14)
	v_lshlrev_b32_e32 v143, 16, v94
	v_lshlrev_b32_e32 v142, 16, v90
	s_waitcnt lgkmcnt(8)
	v_mov_b32_e32 v144, v118
	ds_read_b128 v[138:141], v89 offset:12576
	s_waitcnt lgkmcnt(1)
	v_mov_b32_e32 v145, v134
	v_pk_mul_f32 v[142:143], v[144:145], v[142:143]
	v_mov_b32_e32 v134, v119
	v_add_f32_e32 v102, v102, v142
	v_add_f32_e32 v144, v102, v143
	v_and_b32_e32 v143, 0xffff0000, v94
	v_and_b32_e32 v142, 0xffff0000, v90
	v_pk_mul_f32 v[118:119], v[134:135], v[142:143]
	v_lshlrev_b32_e32 v102, 16, v91
	v_add_f32_e32 v90, v103, v118
	v_add_f32_e32 v134, v90, v119
	v_lshlrev_b32_e32 v103, 16, v95
	v_mov_b32_e32 v118, v120
	v_mov_b32_e32 v119, v136
	v_pk_mul_f32 v[102:103], v[118:119], v[102:103]
	v_and_b32_e32 v95, 0xffff0000, v95
	v_add_f32_e32 v90, v104, v102
	v_and_b32_e32 v94, 0xffff0000, v91
	v_mov_b32_e32 v136, v121
	v_add_f32_e32 v135, v90, v103
	v_pk_mul_f32 v[90:91], v[136:137], v[94:95]
	v_mov_b32_e32 v94, v122
	v_add_f32_e32 v90, v105, v90
	v_add_f32_e32 v136, v90, v91
	v_lshlrev_b32_e32 v91, 16, v96
	v_lshlrev_b32_e32 v90, 16, v92
	s_waitcnt lgkmcnt(0)
	v_mov_b32_e32 v95, v138
	v_pk_mul_f32 v[90:91], v[94:95], v[90:91]
	v_mov_b32_e32 v138, v123
	v_add_f32_e32 v90, v106, v90
	v_add_f32_e32 v122, v90, v91
	v_and_b32_e32 v91, 0xffff0000, v96
	v_and_b32_e32 v90, 0xffff0000, v92
	v_pk_mul_f32 v[90:91], v[138:139], v[90:91]
	v_mov_b32_e32 v94, v124
	v_add_f32_e32 v90, v107, v90
	v_add_f32_e32 v123, v90, v91
	v_lshlrev_b32_e32 v91, 16, v97
	v_lshlrev_b32_e32 v90, 16, v93
	v_mov_b32_e32 v95, v140
	v_pk_mul_f32 v[90:91], v[94:95], v[90:91]
	v_mov_b32_e32 v140, v125
	v_add_f32_e32 v90, v108, v90
	v_add_f32_e32 v108, v90, v91
	v_and_b32_e32 v91, 0xffff0000, v97
	v_and_b32_e32 v90, 0xffff0000, v93
	v_pk_mul_f32 v[90:91], v[140:141], v[90:91]
	v_lshlrev_b32_e32 v103, 16, v98
	v_add_f32_e32 v90, v109, v90
	v_add_f32_e32 v124, v90, v91
	ds_read_b128 v[90:93], v89 offset:12608
	ds_read_b128 v[94:97], v89 offset:12640
	v_lshlrev_b32_e32 v102, 16, v82
	v_mov_b32_e32 v104, v126
	s_and_b32 s4, s49, 0x1ffffe00
	s_waitcnt lgkmcnt(1)
	v_mov_b32_e32 v105, v90
	v_pk_mul_f32 v[102:103], v[104:105], v[102:103]
	s_lshl_b32 s5, s2, 5
	v_add_f32_e32 v90, v110, v102
	v_add_f32_e32 v125, v90, v103
	v_and_b32_e32 v103, 0xffff0000, v98
	v_and_b32_e32 v102, 0xffff0000, v82
	v_mov_b32_e32 v90, v127
	v_pk_mul_f32 v[90:91], v[90:91], v[102:103]
	v_mov_b32_e32 v102, v128
	v_add_f32_e32 v82, v111, v90
	v_add_f32_e32 v126, v82, v91
	v_lshlrev_b32_e32 v91, 16, v99
	v_lshlrev_b32_e32 v90, 16, v83
	v_mov_b32_e32 v103, v92
	v_pk_mul_f32 v[90:91], v[102:103], v[90:91]
	v_mov_b32_e32 v92, v129
	v_add_f32_e32 v82, v112, v90
	v_add_f32_e32 v127, v82, v91
	v_and_b32_e32 v91, 0xffff0000, v99
	v_and_b32_e32 v90, 0xffff0000, v83
	v_pk_mul_f32 v[82:83], v[92:93], v[90:91]
	v_mov_b32_e32 v90, v130
	v_add_f32_e32 v82, v113, v82
	v_add_f32_e32 v128, v82, v83
	v_lshlrev_b32_e32 v83, 16, v100
	v_lshlrev_b32_e32 v82, 16, v84
	s_waitcnt lgkmcnt(0)
; #define LAS __attribute__((address_space(3)))
; template <int PASS>
; __device__ __forceinline__ void lru_unit(const LruPtrs& args, LAS unsigned char* lds, int chunk, int bl, int g, int ck) {
;     ...
;         for (int k = 0; k < 4; ++k)
; #pragma unroll
;             for (int q = 0; q < 8; ++q) xw[k][q] = *(const LAS v2u*)(XT + (n + k) * 68 + 8 * q + 4 * hi);
;         float xc[8][4];
; #pragma unroll
;         for (int q = 0; q < 8; ++q) { const f32x4 bb = *(const LAS f32x4*)(PRM + 4 * 64 + 8 * q + 4 * hi);
; #pragma unroll
;             for (int p = 0; p < 4; ++p) xc[q][p] = bb[p]; }
; #pragma unroll
;         for (int k = 0; k < 4; ++k) {
; #pragma unroll
;             for (int q = 0; q < 8; ++q) { const f32x4 cw = *(const LAS f32x4*)(PRM + k * 64 + 8 * q + 4 * hi);
;                 xc[q][0] += cw[0] * pg8::bf_lo(xw[k][q].x); xc[q][1] += cw[1] * pg8::bf_hi(xw[k][q].x); xc[q][2] += cw[2] * pg8::bf_lo(xw[k][q].y); xc[q][3] += cw[3] * pg8::bf_hi(xw[k][q].y); }
	v_mov_b32_e32 v91, v94
	v_pk_mul_f32 v[82:83], v[90:91], v[82:83]
	v_mov_b32_e32 v94, v131
	v_add_f32_e32 v82, v114, v82
	v_add_f32_e32 v129, v82, v83
	v_and_b32_e32 v83, 0xffff0000, v100
	v_and_b32_e32 v82, 0xffff0000, v84
	v_pk_mul_f32 v[82:83], v[94:95], v[82:83]
	v_mov_b32_e32 v90, v132
	v_add_f32_e32 v82, v115, v82
	v_add_f32_e32 v130, v82, v83
	v_lshlrev_b32_e32 v83, 16, v101
	v_lshlrev_b32_e32 v82, 16, v85
	v_mov_b32_e32 v91, v96
	v_pk_mul_f32 v[82:83], v[90:91], v[82:83]
	v_mov_b32_e32 v96, v133
	v_add_f32_e32 v82, v116, v82
	v_add_f32_e32 v131, v82, v83
	v_and_b32_e32 v83, 0xffff0000, v101
	v_and_b32_e32 v82, 0xffff0000, v85
	v_pk_mul_f32 v[82:83], v[96:97], v[82:83]
	v_lshlrev_b32_e32 v91, 16, v54
	v_add_f32_e32 v82, v117, v82
	v_add_f32_e32 v117, v82, v83
	ds_read_b128 v[82:85], v89 offset:12672
	ds_read_b128 v[94:97], v89 offset:12704
	v_lshlrev_b32_e32 v90, 16, v50
	v_mov_b32_e32 v92, v78
	s_or_b32 s4, s5, s4
	s_waitcnt lgkmcnt(1)
	v_mov_b32_e32 v93, v82
	v_pk_mul_f32 v[90:91], v[92:93], v[90:91]
	v_mov_b32_e32 v82, v79
	v_add_f32_e32 v74, v74, v90
	v_add_f32_e32 v132, v74, v91
	v_and_b32_e32 v91, 0xffff0000, v54
	v_and_b32_e32 v90, 0xffff0000, v50
	v_pk_mul_f32 v[78:79], v[82:83], v[90:91]
	v_lshlrev_b32_e32 v74, 16, v51
	v_add_f32_e32 v50, v75, v78
	v_add_f32_e32 v133, v50, v79
	v_lshlrev_b32_e32 v75, 16, v55
	v_mov_b32_e32 v78, v80
	v_mov_b32_e32 v79, v84
	v_pk_mul_f32 v[74:75], v[78:79], v[74:75]
	v_and_b32_e32 v55, 0xffff0000, v55
	v_add_f32_e32 v50, v76, v74
	v_and_b32_e32 v54, 0xffff0000, v51
	v_mov_b32_e32 v84, v81
	v_add_f32_e32 v92, v50, v75
	v_pk_mul_f32 v[50:51], v[84:85], v[54:55]
	v_mov_b32_e32 v74, v62
	v_add_f32_e32 v50, v77, v50
	v_add_f32_e32 v54, v50, v51
	v_lshlrev_b32_e32 v51, 16, v56
	v_lshlrev_b32_e32 v50, 16, v52
	s_waitcnt lgkmcnt(0)
	v_mov_b32_e32 v75, v94
	v_pk_mul_f32 v[50:51], v[74:75], v[50:51]
	v_and_b32_e32 v75, 0xffff0000, v56
	v_and_b32_e32 v74, 0xffff0000, v52
	v_mov_b32_e32 v94, v63
	v_add_f32_e32 v50, v58, v50
	v_pk_mul_f32 v[62:63], v[94:95], v[74:75]
	v_add_f32_e32 v51, v50, v51
	v_add_f32_e32 v50, v59, v62
	v_add_f32_e32 v52, v50, v63
	v_lshlrev_b32_e32 v59, 16, v57
	v_lshlrev_b32_e32 v58, 16, v53
	v_mov_b32_e32 v62, v64
	v_mov_b32_e32 v63, v96
	v_and_b32_e32 v57, 0xffff0000, v57
	v_and_b32_e32 v56, 0xffff0000, v53
	v_mov_b32_e32 v96, v65
	v_pk_mul_f32 v[58:59], v[62:63], v[58:59]
	v_pk_mul_f32 v[56:57], v[96:97], v[56:57]
	v_add_f32_e32 v50, v60, v58
	v_add_f32_e32 v53, v61, v56
	v_add_f32_e32 v50, v50, v59
	v_add_f32_e32 v53, v53, v57
	ds_read_b128 v[56:59], v89 offset:12736
	ds_read_b128 v[74:77], v89 offset:12768
	v_lshlrev_b32_e32 v61, 16, v6
	v_lshlrev_b32_e32 v60, 16, v2
	v_mov_b32_e32 v62, v46
	s_waitcnt lgkmcnt(1)
	v_mov_b32_e32 v63, v56
	v_pk_mul_f32 v[60:61], v[62:63], v[60:61]
	v_mov_b32_e32 v56, v47
	v_add_f32_e32 v42, v42, v60
	v_add_f32_e32 v94, v42, v61
	v_and_b32_e32 v61, 0xffff0000, v6
	v_and_b32_e32 v60, 0xffff0000, v2
	v_pk_mul_f32 v[46:47], v[56:57], v[60:61]
	v_lshlrev_b32_e32 v42, 16, v3
	v_add_f32_e32 v2, v43, v46
	v_add_f32_e32 v93, v2, v47
	v_lshlrev_b32_e32 v43, 16, v7
	v_mov_b32_e32 v46, v48
	v_mov_b32_e32 v47, v58
	v_pk_mul_f32 v[42:43], v[46:47], v[42:43]
	v_and_b32_e32 v7, 0xffff0000, v7
	v_add_f32_e32 v2, v44, v42
	v_and_b32_e32 v6, 0xffff0000, v3
	v_mov_b32_e32 v58, v49
	v_add_f32_e32 v116, v2, v43
	v_pk_mul_f32 v[2:3], v[58:59], v[6:7]
	v_lshlrev_b32_e32 v7, 16, v38
	v_add_f32_e32 v2, v45, v2
	ds_read_b128 v[56:59], v89 offset:12800
	ds_read_b128 v[60:63], v89 offset:12832
	ds_read_b128 v[96:99], v89 offset:12864
	ds_read_b128 v[118:121], v89 offset:12896
	ds_read_b128 v[46:49], v89 offset:12928
	ds_read_b128 v[42:45], v89 offset:12960
	ds_read_b128 v[82:85], v89 offset:12992
	ds_read_b128 v[78:81], v89 offset:13024
	ds_read_b128 v[100:103], v89 offset:13056
	v_lshlrev_b32_e32 v6, 16, v34
	s_waitcnt lgkmcnt(8)
	v_mov_b32_e32 v64, v56
	v_mov_b32_e32 v56, v58
	ds_read_b128 v[104:107], v89 offset:13088
	s_waitcnt lgkmcnt(1)
	v_mov_b32_e32 v65, v100
	v_pk_mul_f32 v[6:7], v[64:65], v[6:7]
	v_mov_b32_e32 v100, v57
	v_add_f32_e32 v6, v144, v6
	v_add_f32_e32 v115, v6, v7
	v_and_b32_e32 v7, 0xffff0000, v38
	v_and_b32_e32 v6, 0xffff0000, v34
	v_pk_mul_f32 v[6:7], v[100:101], v[6:7]
	v_mov_b32_e32 v57, v102
	v_add_f32_e32 v6, v134, v6
	v_add_f32_e32 v114, v6, v7
	v_lshlrev_b32_e32 v7, 16, v39
	v_lshlrev_b32_e32 v6, 16, v35
	v_pk_mul_f32 v[6:7], v[56:57], v[6:7]
	v_mov_b32_e32 v102, v59
	v_add_f32_e32 v6, v135, v6
	v_add_f32_e32 v113, v6, v7
	v_and_b32_e32 v7, 0xffff0000, v39
	v_and_b32_e32 v6, 0xffff0000, v35
	v_pk_mul_f32 v[6:7], v[102:103], v[6:7]
	v_mov_b32_e32 v34, v60
	v_add_f32_e32 v6, v136, v6
	v_add_f32_e32 v112, v6, v7
	v_lshlrev_b32_e32 v7, 16, v40
	v_lshlrev_b32_e32 v6, 16, v36
	s_waitcnt lgkmcnt(0)
	v_mov_b32_e32 v35, v104
	v_pk_mul_f32 v[6:7], v[34:35], v[6:7]
	v_mov_b32_e32 v104, v61
	v_add_f32_e32 v6, v122, v6
	v_add_f32_e32 v111, v6, v7
	v_and_b32_e32 v7, 0xffff0000, v40
	v_and_b32_e32 v6, 0xffff0000, v36
	v_pk_mul_f32 v[6:7], v[104:105], v[6:7]
	v_mov_b32_e32 v34, v62
	v_add_f32_e32 v6, v123, v6
	v_add_f32_e32 v110, v6, v7
	v_lshlrev_b32_e32 v7, 16, v41
	v_lshlrev_b32_e32 v6, 16, v37
	v_mov_b32_e32 v35, v106
	v_pk_mul_f32 v[6:7], v[34:35], v[6:7]
	v_mov_b32_e32 v106, v63
	v_add_f32_e32 v6, v108, v6
	v_add_f32_e32 v109, v6, v7
	v_and_b32_e32 v6, 0xffff0000, v37
	ds_read_b128 v[34:37], v89 offset:13120
	v_and_b32_e32 v7, 0xffff0000, v41
	v_pk_mul_f32 v[6:7], v[106:107], v[6:7]
	v_mov_b32_e32 v56, v96
	v_add_f32_e32 v6, v124, v6
	v_add_f32_e32 v100, v6, v7
	v_lshlrev_b32_e32 v7, 16, v30
	v_lshlrev_b32_e32 v6, 16, v26
	ds_read_b128 v[38:41], v89 offset:13152
	s_waitcnt lgkmcnt(1)
; __device__ __forceinline__ unsigned cvt_pk_bf16(float lo, float hi) { unsigned r; asm volatile("v_cvt_pk_bf16_f32 %0, %1, %2" : "=v"(r) : "v"(lo), "v"(hi)); return r; }
; #define GAS __attribute__((address_space(1)))
; #define LAS __attribute__((address_space(3)))
; template <int PASS>
; __device__ __forceinline__ void lru_unit(const LruPtrs& args, LAS unsigned char* lds, int chunk, int bl, int g, int ck) {
;     ...
;         for (int k = 0; k < 4; ++k) {
; #pragma unroll
;             for (int q = 0; q < 8; ++q) { const f32x4 cw = *(const LAS f32x4*)(PRM + k * 64 + 8 * q + 4 * hi);
;                 xc[q][0] += cw[0] * pg8::bf_lo(xw[k][q].x); xc[q][1] += cw[1] * pg8::bf_hi(xw[k][q].x); xc[q][2] += cw[2] * pg8::bf_lo(xw[k][q].y); xc[q][3] += cw[3] * pg8::bf_hi(xw[k][q].y); }
;         }
;         f32x16 ar[2], ai_[2];
; #pragma unroll
;         for (int rb = 0; rb < 2; ++rb) { ar[rb] = f32x16{}; ai_[rb] = f32x16{}; }
;         const GAS bf16* wrf = (const GAS bf16*)(ws + WS_WRF) + (size_t)g * (2 * 2 * 4 * 64 * 8) + lane * 8;
; #pragma unroll
;         for (int ks = 0; ks < 4; ++ks) {
;             v4u bw; bw.x = pg8::cvt_pk_bf16(xc[2 * ks][0], xc[2 * ks][1]); bw.y = pg8::cvt_pk_bf16(xc[2 * ks][2], xc[2 * ks][3]); bw.z = pg8::cvt_pk_bf16(xc[2 * ks + 1][0], xc[2 * ks + 1][1]); bw.w = pg8::cvt_pk_bf16(xc[2 * ks + 1][2], xc[2 * ks + 1][3]);
;             const bf16x8 bfr = __builtin_bit_cast(bf16x8, bw);
; #pragma unroll
;             for (int rb = 0; rb < 2; ++rb) {
;                 const bf16x8 wr_ = __builtin_bit_cast(bf16x8, *(const GAS v4u*)(wrf + ((0 * 2 + rb) * 4 + ks) * 512));
	v_mov_b32_e32 v57, v34
	v_pk_mul_f32 v[6:7], v[56:57], v[6:7]
	v_mov_b32_e32 v34, v97
	v_add_f32_e32 v6, v125, v6
	v_add_f32_e32 v106, v6, v7
	v_and_b32_e32 v7, 0xffff0000, v30
	v_and_b32_e32 v6, 0xffff0000, v26
	v_pk_mul_f32 v[6:7], v[34:35], v[6:7]
	v_mov_b32_e32 v34, v98
	v_add_f32_e32 v6, v126, v6
	v_add_f32_e32 v103, v6, v7
	v_lshlrev_b32_e32 v7, 16, v31
	v_lshlrev_b32_e32 v6, 16, v27
	v_mov_b32_e32 v35, v36
	v_pk_mul_f32 v[6:7], v[34:35], v[6:7]
	v_mov_b32_e32 v36, v99
	v_add_f32_e32 v6, v127, v6
	v_add_f32_e32 v102, v6, v7
	v_and_b32_e32 v7, 0xffff0000, v31
	v_and_b32_e32 v6, 0xffff0000, v27
	v_pk_mul_f32 v[6:7], v[36:37], v[6:7]
	v_mov_b32_e32 v26, v118
	v_add_f32_e32 v6, v128, v6
	v_add_f32_e32 v99, v6, v7
	v_lshlrev_b32_e32 v7, 16, v32
	v_lshlrev_b32_e32 v6, 16, v28
	s_waitcnt lgkmcnt(0)
	v_mov_b32_e32 v27, v38
	v_pk_mul_f32 v[6:7], v[26:27], v[6:7]
	v_mov_b32_e32 v38, v119
	v_add_f32_e32 v6, v129, v6
	v_add_f32_e32 v97, v6, v7
	v_and_b32_e32 v7, 0xffff0000, v32
	v_and_b32_e32 v6, 0xffff0000, v28
	v_pk_mul_f32 v[6:7], v[38:39], v[6:7]
	v_mov_b32_e32 v26, v120
	v_add_f32_e32 v6, v130, v6
	v_add_f32_e32 v96, v6, v7
	v_lshlrev_b32_e32 v7, 16, v33
	v_lshlrev_b32_e32 v6, 16, v29
	v_mov_b32_e32 v27, v40
	v_pk_mul_f32 v[6:7], v[26:27], v[6:7]
	v_mov_b32_e32 v40, v121
	v_add_f32_e32 v6, v131, v6
	v_add_f32_e32 v95, v6, v7
	v_and_b32_e32 v6, 0xffff0000, v29
	ds_read_b128 v[26:29], v89 offset:13184
	v_and_b32_e32 v7, 0xffff0000, v33
	v_pk_mul_f32 v[6:7], v[40:41], v[6:7]
	v_mov_b32_e32 v34, v46
	v_add_f32_e32 v6, v117, v6
	v_add_f32_e32 v90, v6, v7
	v_lshlrev_b32_e32 v7, 16, v22
	v_lshlrev_b32_e32 v6, 16, v18
	ds_read_b128 v[30:33], v89 offset:13216
	s_waitcnt lgkmcnt(1)
	v_mov_b32_e32 v35, v26
	v_pk_mul_f32 v[6:7], v[34:35], v[6:7]
	v_mov_b32_e32 v26, v47
	v_add_f32_e32 v6, v132, v6
	v_add_f32_e32 v91, v6, v7
	v_and_b32_e32 v7, 0xffff0000, v22
	v_and_b32_e32 v6, 0xffff0000, v18
	v_pk_mul_f32 v[6:7], v[26:27], v[6:7]
	v_mov_b32_e32 v26, v48
	v_add_f32_e32 v6, v133, v6
	v_add_f32_e32 v107, v6, v7
	v_lshlrev_b32_e32 v7, 16, v23
	v_lshlrev_b32_e32 v6, 16, v19
	v_mov_b32_e32 v27, v28
	v_pk_mul_f32 v[6:7], v[26:27], v[6:7]
	v_mov_b32_e32 v28, v49
	v_add_f32_e32 v6, v92, v6
	v_add_f32_e32 v108, v6, v7
	v_and_b32_e32 v7, 0xffff0000, v23
	v_and_b32_e32 v6, 0xffff0000, v19
	s_or_b32 s4, s4, s45
	v_pk_mul_f32 v[6:7], v[28:29], v[6:7]
	s_lshl_b32 s4, s4, 3
	s_ashr_i32 s5, s48, 31
	v_add_f32_e32 v6, v54, v6
	s_add_u32 s4, s48, s4
	v_add_f32_e32 v105, v6, v7
	v_lshlrev_b32_e32 v7, 16, v24
	v_lshlrev_b32_e32 v6, 16, v20
	v_mov_b32_e32 v18, v42
	s_waitcnt lgkmcnt(0)
	v_mov_b32_e32 v19, v30
	s_addc_u32 s5, s5, 0
	v_pk_mul_f32 v[6:7], v[18:19], v[6:7]
	s_lshl_b64 s[4:5], s[4:5], 13
	v_add_f32_e32 v6, v51, v6
	s_add_u32 s4, s42, s4
	v_add_f32_e32 v104, v6, v7
	v_and_b32_e32 v7, 0xffff0000, v24
	v_and_b32_e32 v6, 0xffff0000, v20
	v_mov_b32_e32 v30, v43
	s_addc_u32 s5, s43, s5
	s_lshl_b32 s2, s2, 14
	v_pk_mul_f32 v[6:7], v[30:31], v[6:7]
	s_add_u32 s48, s42, s2
	v_add_f32_e32 v6, v52, v6
	v_lshlrev_b32_e32 v0, 4, v86
	s_addc_u32 s49, s43, 0
	v_add_f32_e32 v101, v6, v7
	v_lshlrev_b32_e32 v7, 16, v25
	v_lshlrev_b32_e32 v6, 16, v21
	v_mov_b32_e32 v18, v44
	v_mov_b32_e32 v19, v32
	v_lshl_add_u64 v[38:39], s[48:49], 0, v[0:1]
	s_mov_b32 s2, 0x2501000
	v_pk_mul_f32 v[6:7], v[18:19], v[6:7]
	v_add_co_u32_e32 v166, vcc, s2, v38
	v_add_f32_e32 v6, v50, v6
	s_nop 0
	v_addc_co_u32_e32 v167, vcc, 0, v39, vcc
	v_add_f32_e32 v98, v6, v7
	v_and_b32_e32 v7, 0xffff0000, v25
	v_and_b32_e32 v6, 0xffff0000, v21
	v_mov_b32_e32 v32, v45
	ds_read_b128 v[118:121], v89 offset:13248
	ds_read_b128 v[122:125], v89 offset:13280
	v_cvt_pk_bf16_f32 v126, v115, v114
	v_cvt_pk_bf16_f32 v127, v113, v112
	v_cvt_pk_bf16_f32 v128, v111, v110
	v_cvt_pk_bf16_f32 v129, v109, v100
	global_load_dwordx4 v[34:37], v[166:167], off offset:-4096
	global_load_dwordx4 v[130:133], v[166:167], off
	v_pk_mul_f32 v[6:7], v[32:33], v[6:7]
	v_add_f32_e32 v117, v2, v3
	v_add_f32_e32 v6, v53, v6
	v_add_f32_e32 v92, v6, v7
	v_lshlrev_b32_e32 v3, 16, v8
	v_lshlrev_b32_e32 v2, 16, v4
	v_mov_b32_e32 v6, v14
	v_mov_b32_e32 v7, v74
	v_pk_mul_f32 v[2:3], v[6:7], v[2:3]
	s_mov_b32 s2, 0x2503000
	v_add_f32_e32 v2, v10, v2
	v_add_f32_e32 v174, v2, v3
	v_and_b32_e32 v3, 0xffff0000, v8
	v_and_b32_e32 v2, 0xffff0000, v4
	v_mov_b32_e32 v74, v15
	v_add_co_u32_e32 v168, vcc, s2, v38
	v_pk_mul_f32 v[2:3], v[74:75], v[2:3]
	v_lshlrev_b32_e32 v19, 16, v70
	v_lshlrev_b32_e32 v18, 16, v66
	v_mov_b32_e32 v20, v82
	s_waitcnt lgkmcnt(1)
	v_mov_b32_e32 v21, v118
	v_addc_co_u32_e32 v169, vcc, 0, v39, vcc
	v_add_f32_e32 v2, v11, v2
	v_pk_mul_f32 v[18:19], v[20:21], v[18:19]
	global_load_dwordx4 v[56:59], v[168:169], off offset:-4096
	global_load_dwordx4 v[26:29], v[168:169], off
	v_cvt_pk_bf16_f32 v134, v106, v103
	v_cvt_pk_bf16_f32 v135, v102, v99
	v_cvt_pk_bf16_f32 v136, v97, v96
	v_cvt_pk_bf16_f32 v137, v95, v90
	global_load_dwordx4 v[146:149], v[166:167], off offset:1024
	global_load_dwordx4 v[150:153], v[168:169], off offset:1024
	v_add_f32_e32 v175, v2, v3
	v_lshlrev_b32_e32 v3, 16, v9
	v_lshlrev_b32_e32 v2, 16, v5
	v_mov_b32_e32 v6, v16
	v_mov_b32_e32 v7, v76
	v_add_f32_e32 v18, v94, v18
	v_pk_mul_f32 v[2:3], v[6:7], v[2:3]
	v_add_f32_e32 v94, v18, v19
	v_and_b32_e32 v19, 0xffff0000, v70
	v_and_b32_e32 v18, 0xffff0000, v66
	v_mov_b32_e32 v118, v83
	v_add_f32_e32 v2, v12, v2
	v_pk_mul_f32 v[74:75], v[118:119], v[18:19]
	v_add_f32_e32 v176, v2, v3
	v_and_b32_e32 v3, 0xffff0000, v9
	v_and_b32_e32 v2, 0xffff0000, v5
	v_mov_b32_e32 v76, v17
	v_add_f32_e32 v66, v93, v74
	v_pk_mul_f32 v[2:3], v[76:77], v[2:3]
	v_add_f32_e32 v93, v66, v75
	v_lshlrev_b32_e32 v75, 16, v71
	v_lshlrev_b32_e32 v74, 16, v67
	v_mov_b32_e32 v76, v84
	v_mov_b32_e32 v77, v120
	s_mov_b32 s2, 0x2502000
	v_pk_mul_f32 v[74:75], v[76:77], v[74:75]
	s_mov_b64 s[48:49], 0x2500000
	v_add_co_u32_e32 v172, vcc, s2, v38
	v_add_f32_e32 v66, v116, v74
	v_and_b32_e32 v71, 0xffff0000, v71
	v_and_b32_e32 v70, 0xffff0000, v67
	v_mov_b32_e32 v120, v85
	v_lshl_add_u64 v[170:171], v[38:39], 0, s[48:49]
	v_addc_co_u32_e32 v173, vcc, 0, v39, vcc
	v_add_f32_e32 v83, v66, v75
	v_pk_mul_f32 v[66:67], v[120:121], v[70:71]
	global_load_dwordx4 v[138:141], v[170:171], off offset:1024
	global_load_dwordx4 v[142:145], v[172:173], off offset:1024
	v_cvt_pk_bf16_f32 v154, v91, v107
	v_cvt_pk_bf16_f32 v155, v108, v105
	v_cvt_pk_bf16_f32 v156, v104, v101
	v_cvt_pk_bf16_f32 v157, v98, v92
	v_add_f32_e32 v66, v117, v66
	global_load_dwordx4 v[116:119], v[166:167], off offset:2048
	v_add_f32_e32 v82, v66, v67
	v_lshlrev_b32_e32 v67, 16, v72
	v_lshlrev_b32_e32 v66, 16, v68
	v_mov_b32_e32 v70, v78
	s_waitcnt lgkmcnt(0)
; #define GAS __attribute__((address_space(1)))
; template <int PASS>
; __device__ __forceinline__ void lru_unit(const LruPtrs& args, LAS unsigned char* lds, int chunk, int bl, int g, int ck) {
;     ...
;         for (int k = 0; k < 4; ++k) {
; #pragma unroll
;             for (int q = 0; q < 8; ++q) { const f32x4 cw = *(const LAS f32x4*)(PRM + k * 64 + 8 * q + 4 * hi);
;                 xc[q][0] += cw[0] * pg8::bf_lo(xw[k][q].x); xc[q][1] += cw[1] * pg8::bf_hi(xw[k][q].x); xc[q][2] += cw[2] * pg8::bf_lo(xw[k][q].y); xc[q][3] += cw[3] * pg8::bf_hi(xw[k][q].y); }
;         }
;         f32x16 ar[2], ai_[2];
; #pragma unroll
;         for (int rb = 0; rb < 2; ++rb) { ar[rb] = f32x16{}; ai_[rb] = f32x16{}; }
;         const GAS bf16* wrf = (const GAS bf16*)(ws + WS_WRF) + (size_t)g * (2 * 2 * 4 * 64 * 8) + lane * 8;
; #pragma unroll
;         for (int ks = 0; ks < 4; ++ks) {
;             v4u bw; bw.x = pg8::cvt_pk_bf16(xc[2 * ks][0], xc[2 * ks][1]); bw.y = pg8::cvt_pk_bf16(xc[2 * ks][2], xc[2 * ks][3]); bw.z = pg8::cvt_pk_bf16(xc[2 * ks + 1][0], xc[2 * ks + 1][1]); bw.w = pg8::cvt_pk_bf16(xc[2 * ks + 1][2], xc[2 * ks + 1][3]);
;             const bf16x8 bfr = __builtin_bit_cast(bf16x8, bw);
; #pragma unroll
;             for (int rb = 0; rb < 2; ++rb) {
;                 const bf16x8 wr_ = __builtin_bit_cast(bf16x8, *(const GAS v4u*)(wrf + ((0 * 2 + rb) * 4 + ks) * 512));
;                 const bf16x8 wi_ = __builtin_bit_cast(bf16x8, *(const GAS v4u*)(wrf + ((1 * 2 + rb) * 4 + ks) * 512));
;                 ar[rb] = __builtin_amdgcn_mfma_f32_32x32x16_bf16(wr_, bfr, ar[rb], 0, 0, 0);
;                 ai_[rb] = __builtin_amdgcn_mfma_f32_32x32x16_bf16(wi_, bfr, ai_[rb], 0, 0, 0);
;             }
;         }
; #pragma unroll
;         for (int q = 0; q < 8; ++q) {
;             const f32x4 br = *(const LAS f32x4*)(PRM + 5 * 64 + 8 * q + 4 * hi), bi = *(const LAS f32x4*)(PRM + 6 * 64 + 8 * q + 4 * hi), cf = *(const LAS f32x4*)(PRM + 7 * 64 + 8 * q + 4 * hi);
; #pragma unroll
;             for (int p = 0; p < 4; ++p) { const int rb = q >> 2, r = (q & 3) * 4 + p;
;                 const float rr = pg8::sigm(ar[rb][r] + br[p]), ii = pg8::sigm(ai_[rb][r] + bi[p]);
;                 const float a0 = __builtin_amdgcn_exp2f(cf[p] * rr);
;                 av[q][p] = a0; uv[q][p] = __builtin_amdgcn_sqrtf(fmaxf(1.f - a0 * a0, 0.f)) * (ii * xc[q][p]); }
	v_mov_b32_e32 v71, v122
	v_pk_mul_f32 v[66:67], v[70:71], v[66:67]
	v_mov_b32_e32 v122, v79
	v_add_f32_e32 v66, v174, v66
	v_add_f32_e32 v77, v66, v67
	v_and_b32_e32 v67, 0xffff0000, v72
	v_and_b32_e32 v66, 0xffff0000, v68
	v_pk_mul_f32 v[66:67], v[122:123], v[66:67]
	global_load_dwordx4 v[120:123], v[168:169], off offset:2048
	global_load_dwordx4 v[158:161], v[170:171], off offset:2048
	global_load_dwordx4 v[162:165], v[172:173], off offset:2048
	v_add_f32_e32 v66, v175, v66
	v_add_f32_e32 v76, v66, v67
	v_lshlrev_b32_e32 v67, 16, v73
	v_lshlrev_b32_e32 v66, 16, v69
	v_mov_b32_e32 v70, v80
	v_mov_b32_e32 v71, v124
	v_pk_mul_f32 v[66:67], v[70:71], v[66:67]
	v_add_f32_e32 v2, v13, v2
	v_add_f32_e32 v66, v176, v66
	v_add_f32_e32 v74, v66, v67
	v_and_b32_e32 v67, 0xffff0000, v73
	v_and_b32_e32 v66, 0xffff0000, v69
	v_mov_b32_e32 v124, v81
	v_add_f32_e32 v177, v2, v3
	s_waitcnt vmcnt(10)
	v_mfma_f32_32x32x16_bf16 v[2:17], v[130:133], v[126:129], 0
	v_mul_f32_e64 v66, v124, v66
	v_mul_f32_e64 v67, v125, v67
	v_cvt_pk_bf16_f32 v78, v94, v93
	v_cvt_pk_bf16_f32 v79, v83, v82
	v_cvt_pk_bf16_f32 v80, v77, v76
	s_mov_b32 s2, 0x29c01000
	v_add_f32_e32 v66, v177, v66
	v_add_f32_e32 v75, v66, v67
	v_cvt_pk_bf16_f32 v81, v74, v75
	global_load_dwordx4 v[66:69], v[170:171], off offset:3072
	global_load_dwordx4 v[70:73], v[172:173], off offset:3072
	s_waitcnt vmcnt(9)
	v_mfma_f32_32x32x16_bf16 v[2:17], v[146:149], v[134:137], v[2:17]
	s_waitcnt vmcnt(5)
	v_mfma_f32_32x32x16_bf16 v[2:17], v[116:119], v[154:157], v[2:17]
	global_load_dwordx4 v[116:119], v[166:167], off offset:3072
	v_mfma_f32_32x32x16_bf16 v[18:33], v[26:29], v[126:129], 0
	v_mfma_f32_32x32x16_bf16 v[34:49], v[34:37], v[126:129], 0
	v_mfma_f32_32x32x16_bf16 v[18:33], v[150:153], v[134:137], v[18:33]
	v_mfma_f32_32x32x16_bf16 v[50:65], v[56:59], v[126:129], 0
	ds_read_b128 v[124:127], v89 offset:13568
	ds_read_b128 v[128:131], v89 offset:13600
	v_mfma_f32_32x32x16_bf16 v[34:49], v[138:141], v[134:137], v[34:49]
	s_waitcnt vmcnt(5)
	v_mfma_f32_32x32x16_bf16 v[18:33], v[120:123], v[154:157], v[18:33]
	global_load_dwordx4 v[120:123], v[168:169], off offset:3072
	v_mfma_f32_32x32x16_bf16 v[50:65], v[142:145], v[134:137], v[50:65]
	s_waitcnt vmcnt(5)
	v_mfma_f32_32x32x16_bf16 v[34:49], v[158:161], v[154:157], v[34:49]
	s_waitcnt vmcnt(4)
	v_mfma_f32_32x32x16_bf16 v[50:65], v[162:165], v[154:157], v[50:65]
	s_waitcnt vmcnt(3)
	v_mfma_f32_32x32x16_bf16 v[34:49], v[66:69], v[78:81], v[34:49]
	s_waitcnt vmcnt(2)
	v_mfma_f32_32x32x16_bf16 v[50:65], v[70:73], v[78:81], v[50:65]
	v_lshl_add_u64 v[72:73], s[4:5], 0, v[0:1]
	s_waitcnt lgkmcnt(1)
	s_nop 7
	v_add_f32_e32 v0, v34, v124
	v_mul_f32_e32 v0, 0xbfb8aa3b, v0
	v_exp_f32_e32 v0, v0
	v_add_f32_e32 v35, v35, v125
	v_mul_f32_e32 v35, 0xbfb8aa3b, v35
	v_exp_f32_e32 v35, v35
	s_waitcnt vmcnt(1)
	v_mfma_f32_32x32x16_bf16 v[2:17], v[116:119], v[78:81], v[2:17]
	ds_read_b128 v[116:119], v89 offset:13824
	ds_read_b128 v[132:135], v89 offset:14080
	v_add_f32_e32 v0, 1.0, v0
	v_rcp_f32_e32 v0, v0
	v_add_f32_e32 v35, 1.0, v35
	s_waitcnt lgkmcnt(1)
	v_add_f32_e32 v34, v50, v116
	v_mul_f32_e32 v34, 0xbfb8aa3b, v34
	s_waitcnt lgkmcnt(0)
	v_mul_f32_e32 v0, v132, v0
	v_exp_f32_e32 v34, v34
	v_exp_f32_e32 v66, v0
	v_rcp_f32_e32 v35, v35
	v_add_f32_e32 v50, v51, v117
	v_add_f32_e32 v0, 1.0, v34
	v_fma_f32 v34, -v66, v66, 1.0
	v_rcp_f32_e32 v0, v0
	v_max_f32_e32 v34, 0, v34
	v_mul_f32_e32 v50, 0xbfb8aa3b, v50
	v_mul_f32_e32 v35, v133, v35
	v_sqrt_f32_e32 v34, v34
	v_exp_f32_e32 v50, v50
	v_exp_f32_e32 v68, v35
	v_mul_f32_e32 v0, v115, v0
	v_mul_f32_e32 v67, v0, v34
	v_add_f32_e32 v0, 1.0, v50
	v_fma_f32 v34, -v68, v68, 1.0
	v_add_f32_e32 v35, v36, v126
	v_rcp_f32_e32 v0, v0
	v_mul_f32_e32 v35, 0xbfb8aa3b, v35
	v_max_f32_e32 v34, 0, v34
	v_exp_f32_e32 v35, v35
	v_sqrt_f32_e32 v36, v34
	v_mul_f32_e32 v0, v114, v0
	v_add_f32_e32 v38, v38, v128
	v_add_f32_e32 v34, 1.0, v35
	v_mul_f32_e32 v69, v0, v36
	v_add_f32_e32 v36, v37, v127
	v_rcp_f32_e32 v34, v34
	v_mul_f32_e32 v36, 0xbfb8aa3b, v36
	v_exp_f32_e32 v36, v36
	v_add_f32_e32 v35, v52, v118
	v_mul_f32_e32 v35, 0xbfb8aa3b, v35
	v_mul_f32_e32 v34, v134, v34
	v_exp_f32_e32 v35, v35
	v_exp_f32_e32 v34, v34
	v_add_f32_e32 v36, 1.0, v36
	v_rcp_f32_e32 v36, v36
	v_mul_f32_e32 v38, 0xbfb8aa3b, v38
	v_exp_f32_e32 v38, v38
	v_add_f32_e32 v0, 1.0, v35
	v_fma_f32 v35, -v34, v34, 1.0
	v_add_f32_e32 v37, v53, v119
	ds_read_b128 v[136:139], v89 offset:13856
	ds_read_b128 v[140:143], v89 offset:14112
	v_rcp_f32_e32 v0, v0
	v_max_f32_e32 v35, 0, v35
	v_mul_f32_e32 v37, 0xbfb8aa3b, v37
	v_mul_f32_e32 v36, v135, v36
	v_sqrt_f32_e32 v35, v35
	v_exp_f32_e32 v37, v37
	v_exp_f32_e32 v36, v36
	v_add_f32_e32 v38, 1.0, v38
	v_add_f32_e32 v39, v39, v129
	v_rcp_f32_e32 v38, v38
	v_mul_f32_e32 v39, 0xbfb8aa3b, v39
	v_exp_f32_e32 v39, v39
	v_mul_f32_e32 v0, v113, v0
	v_mul_f32_e32 v35, v0, v35
	v_add_f32_e32 v0, 1.0, v37
	v_fma_f32 v37, -v36, v36, 1.0
	s_waitcnt lgkmcnt(1)
	v_add_f32_e32 v50, v54, v136
	v_rcp_f32_e32 v0, v0
	v_max_f32_e32 v37, 0, v37
	v_mul_f32_e32 v50, 0xbfb8aa3b, v50
	s_waitcnt lgkmcnt(0)
	v_mul_f32_e32 v38, v140, v38
	v_sqrt_f32_e32 v37, v37
	v_exp_f32_e32 v51, v50
	v_exp_f32_e32 v50, v38
	v_add_f32_e32 v39, 1.0, v39
	v_rcp_f32_e32 v39, v39
	v_mul_f32_e32 v0, v112, v0
	v_mul_f32_e32 v37, v0, v37
	v_add_f32_e32 v0, 1.0, v51
	v_fma_f32 v38, -v50, v50, 1.0
	v_rcp_f32_e32 v0, v0
	v_max_f32_e32 v38, 0, v38
	v_add_f32_e32 v51, v55, v137
	v_mul_f32_e32 v39, v141, v39
	v_sqrt_f32_e32 v38, v38
	v_mul_f32_e32 v51, 0xbfb8aa3b, v51
	v_exp_f32_e32 v52, v39
	v_add_f32_e32 v39, v40, v130
	v_exp_f32_e32 v53, v51
	v_mul_f32_e32 v39, 0xbfb8aa3b, v39
	v_exp_f32_e32 v39, v39
	v_mul_f32_e32 v0, v111, v0
	v_mul_f32_e32 v51, v0, v38
	v_fma_f32 v38, -v52, v52, 1.0
	v_add_f32_e32 v0, 1.0, v53
	v_max_f32_e32 v38, 0, v38
	v_rcp_f32_e32 v0, v0
	v_sqrt_f32_e32 v40, v38
	v_add_f32_e32 v38, 1.0, v39
	v_rcp_f32_e32 v38, v38
	v_mul_f32_e32 v0, v110, v0
	v_add_f32_e32 v39, v56, v138
	v_mul_f32_e32 v39, 0xbfb8aa3b, v39
	v_mul_f32_e32 v38, v142, v38
	v_mul_f32_e32 v53, v0, v40
	v_add_f32_e32 v40, v41, v131
	s_waitcnt vmcnt(0)
	v_mfma_f32_32x32x16_bf16 v[18:33], v[120:123], v[78:81], v[18:33]
	v_exp_f32_e32 v39, v39
	v_exp_f32_e32 v38, v38
	v_mul_f32_e32 v40, 0xbfb8aa3b, v40
	ds_read_b128 v[78:81], v89 offset:13632
	ds_read_b128 v[110:113], v89 offset:13664
	v_mov_b32_e32 v180, s86
	ds_read_b32 v180, v180 offset:64
	s_waitcnt lgkmcnt(0)
	v_readfirstlane_b32 s100, v180
	s_sub_i32 s100, s100, 32
	s_cmp_ge_u32 s100, 0x400
	s_cbranch_scc1 .Llpf_skip
; __device__ __forceinline__ float sigm(float x) { return __builtin_amdgcn_rcpf(1.f + __expf(-x)); }
; #define GAS __attribute__((address_space(1)))
; #define LAS __attribute__((address_space(3)))
; template <int PASS>
; __device__ __forceinline__ void lru_unit(const LruPtrs& args, LAS unsigned char* lds, int chunk, int bl, int g, int ck) {
;     ...
;             for (int i = 0; i < 5; ++i) { const int idx = lane + 64 * i, r = idx >> 3, ch = idx & 7; const int ts = tl0 - 3 + r;
;                 xv[i] = (v4u){0u, 0u, 0u, 0u};
;                 if (r < 35 && ts >= 0) xv[i] = *(const GAS v4u*)(Z + ((size_t)bl * T + ts) * LDZ + ZC_AX + g * 64 + ch * 8); }
;     ...
; #pragma unroll
;         for (int q = 0; q < 8; ++q) {
;             const f32x4 br = *(const LAS f32x4*)(PRM + 5 * 64 + 8 * q + 4 * hi), bi = *(const LAS f32x4*)(PRM + 6 * 64 + 8 * q + 4 * hi), cf = *(const LAS f32x4*)(PRM + 7 * 64 + 8 * q + 4 * hi);
; #pragma unroll
;             for (int p = 0; p < 4; ++p) { const int rb = q >> 2, r = (q & 3) * 4 + p;
;                 const float rr = pg8::sigm(ar[rb][r] + br[p]), ii = pg8::sigm(ai_[rb][r] + bi[p]);
;                 const float a0 = __builtin_amdgcn_exp2f(cf[p] * rr);
;                 av[q][p] = a0; uv[q][p] = __builtin_amdgcn_sqrtf(fmaxf(1.f - a0 * a0, 0.f)) * (ii * xc[q][p]); }
	s_lshr_b32 s101, s100, 9
	s_lshl_b32 s101, s101, 13
	v_bfe_u32 v181, v236, 3, 3
	v_and_b32_e32 v182, 0x1c0, v236
	v_lshrrev_b32_e32 v182, 1, v182
	v_add3_u32 v181, v181, v182, s101
	s_and_b32 s101, s100, 31
	s_lshl_b32 s101, s101, 8
	v_add_u32_e32 v181, s101, v181
	v_add_u32_e32 v181, -3, v181
	v_max_i32_e32 v181, 0, v181
	s_bfe_u32 s101, s100, 0x40005
	s_lshl_b32 s101, s101, 7
	v_and_b32_e32 v182, 7, v236
	v_lshlrev_b32_e32 v182, 4, v182
	v_add_u32_e32 v182, s101, v182
	v_lshl_add_u32 v181, v181, 11, v182
	s_add_u32 s100, s40, 0x13c00000
	s_addc_u32 s101, s41, 0
	v_add_u32_e32 v183, 0x4000, v181
	v_add_u32_e32 v184, 0x8000, v181
	v_add_u32_e32 v185, 0xc000, v181
	global_load_dwordx4 v[188:191], v181, s[100:101]
	global_load_dwordx4 v[192:195], v183, s[100:101]
	global_load_dwordx4 v[196:199], v184, s[100:101]
	global_load_dwordx4 v[200:203], v185, s[100:101]
.Llpf_skip:
	v_exp_f32_e32 v40, v40
	v_add_f32_e32 v0, 1.0, v39
	v_fma_f32 v39, -v38, v38, 1.0
	v_rcp_f32_e32 v0, v0
	v_max_f32_e32 v39, 0, v39
	v_add_f32_e32 v40, 1.0, v40
	s_waitcnt lgkmcnt(1)
	v_add_f32_e32 v42, v42, v78
	v_sqrt_f32_e32 v39, v39
	v_rcp_f32_e32 v40, v40
	v_mul_f32_e32 v42, 0xbfb8aa3b, v42
	v_exp_f32_e32 v42, v42
	v_mul_f32_e32 v0, v109, v0
	v_add_f32_e32 v41, v57, v139
	v_mul_f32_e32 v41, 0xbfb8aa3b, v41
	v_mul_f32_e32 v39, v0, v39
	v_mul_f32_e32 v0, v143, v40
	v_exp_f32_e32 v41, v41
	v_exp_f32_e32 v40, v0
	ds_read_b128 v[114:117], v89 offset:13888
	ds_read_b128 v[118:121], v89 offset:14144
	v_add_f32_e32 v42, 1.0, v42
	v_add_f32_e32 v43, v43, v79
	v_rcp_f32_e32 v42, v42
	v_mul_f32_e32 v43, 0xbfb8aa3b, v43
	v_exp_f32_e32 v43, v43
	v_add_f32_e32 v0, 1.0, v41
	v_fma_f32 v41, -v40, v40, 1.0
	s_waitcnt lgkmcnt(1)
	v_add_f32_e32 v54, v58, v114
	v_rcp_f32_e32 v0, v0
	v_max_f32_e32 v41, 0, v41
	v_mul_f32_e32 v54, 0xbfb8aa3b, v54
	s_waitcnt lgkmcnt(0)
	v_mul_f32_e32 v42, v118, v42
	v_sqrt_f32_e32 v41, v41
	v_exp_f32_e32 v55, v54
	v_exp_f32_e32 v54, v42
	v_add_f32_e32 v43, 1.0, v43
	v_rcp_f32_e32 v43, v43
	v_mul_f32_e32 v0, v100, v0
	v_mul_f32_e32 v41, v0, v41
	v_add_f32_e32 v0, 1.0, v55
	v_fma_f32 v42, -v54, v54, 1.0
	v_add_f32_e32 v55, v59, v115
	v_rcp_f32_e32 v0, v0
	v_max_f32_e32 v42, 0, v42
	v_mul_f32_e32 v55, 0xbfb8aa3b, v55
	v_mul_f32_e32 v43, v119, v43
	v_sqrt_f32_e32 v42, v42
	v_exp_f32_e32 v57, v55
	v_exp_f32_e32 v56, v43
	v_mul_f32_e32 v0, v106, v0
	v_mul_f32_e32 v55, v0, v42
	v_add_f32_e32 v0, 1.0, v57
	v_fma_f32 v42, -v56, v56, 1.0
	v_add_f32_e32 v43, v44, v80
	v_rcp_f32_e32 v0, v0
	v_mul_f32_e32 v43, 0xbfb8aa3b, v43
	v_max_f32_e32 v42, 0, v42
	v_exp_f32_e32 v43, v43
	v_sqrt_f32_e32 v44, v42
	v_mul_f32_e32 v0, v103, v0
	v_add_f32_e32 v46, v46, v110
	v_add_f32_e32 v42, 1.0, v43
	v_mul_f32_e32 v57, v0, v44
	v_add_f32_e32 v44, v45, v81
	v_rcp_f32_e32 v42, v42
	v_mul_f32_e32 v44, 0xbfb8aa3b, v44
	v_exp_f32_e32 v44, v44
	v_add_f32_e32 v43, v60, v116
	v_mul_f32_e32 v43, 0xbfb8aa3b, v43
	v_mul_f32_e32 v42, v120, v42
	v_exp_f32_e32 v43, v43
	v_exp_f32_e32 v42, v42
	v_add_f32_e32 v44, 1.0, v44
	v_rcp_f32_e32 v44, v44
	v_mul_f32_e32 v46, 0xbfb8aa3b, v46
	v_exp_f32_e32 v46, v46
	v_add_f32_e32 v0, 1.0, v43
	v_fma_f32 v43, -v42, v42, 1.0
	v_add_f32_e32 v45, v61, v117
	ds_read_b128 v[122:125], v89 offset:13920
	ds_read_b128 v[126:129], v89 offset:14176
	v_rcp_f32_e32 v0, v0
	v_max_f32_e32 v43, 0, v43
	v_mul_f32_e32 v45, 0xbfb8aa3b, v45
	v_mul_f32_e32 v44, v121, v44
	v_sqrt_f32_e32 v43, v43
	v_exp_f32_e32 v45, v45
	v_exp_f32_e32 v44, v44
	v_add_f32_e32 v46, 1.0, v46
	v_add_f32_e32 v47, v47, v111
	v_rcp_f32_e32 v46, v46
	v_mul_f32_e32 v47, 0xbfb8aa3b, v47
	v_exp_f32_e32 v47, v47
	v_mul_f32_e32 v0, v102, v0
	v_mul_f32_e32 v43, v0, v43
	v_add_f32_e32 v0, 1.0, v45
	v_fma_f32 v45, -v44, v44, 1.0
	s_waitcnt lgkmcnt(1)
	v_add_f32_e32 v58, v62, v122
	v_rcp_f32_e32 v0, v0
	v_max_f32_e32 v45, 0, v45
	v_mul_f32_e32 v58, 0xbfb8aa3b, v58
	s_waitcnt lgkmcnt(0)
	v_mul_f32_e32 v46, v126, v46
	v_sqrt_f32_e32 v45, v45
	v_exp_f32_e32 v59, v58
	v_exp_f32_e32 v58, v46
	v_add_f32_e32 v47, 1.0, v47
	v_rcp_f32_e32 v47, v47
	v_mul_f32_e32 v0, v99, v0
	v_mul_f32_e32 v45, v0, v45
	v_add_f32_e32 v0, 1.0, v59
	v_fma_f32 v46, -v58, v58, 1.0
	v_rcp_f32_e32 v0, v0
	v_max_f32_e32 v46, 0, v46
	v_add_f32_e32 v59, v63, v123
	v_mul_f32_e32 v47, v127, v47
	v_sqrt_f32_e32 v46, v46
	v_mul_f32_e32 v59, 0xbfb8aa3b, v59
	v_exp_f32_e32 v60, v47
	v_add_f32_e32 v47, v48, v112
	v_exp_f32_e32 v61, v59
	v_mul_f32_e32 v47, 0xbfb8aa3b, v47
	v_exp_f32_e32 v47, v47
	v_mul_f32_e32 v0, v97, v0
	v_mul_f32_e32 v59, v0, v46
	v_fma_f32 v46, -v60, v60, 1.0
	v_add_f32_e32 v0, 1.0, v61
	v_max_f32_e32 v46, 0, v46
	v_rcp_f32_e32 v0, v0
	v_sqrt_f32_e32 v48, v46
	v_add_f32_e32 v46, 1.0, v47
	v_rcp_f32_e32 v46, v46
	v_mul_f32_e32 v0, v96, v0
	v_add_f32_e32 v47, v64, v124
	v_mul_f32_e32 v47, 0xbfb8aa3b, v47
	v_mul_f32_e32 v46, v128, v46
	v_mul_f32_e32 v61, v0, v48
	v_add_f32_e32 v48, v49, v113
	v_exp_f32_e32 v47, v47
	v_exp_f32_e32 v46, v46
	v_mul_f32_e32 v48, 0xbfb8aa3b, v48
	ds_read_b128 v[78:81], v89 offset:13696
	ds_read_b128 v[110:113], v89 offset:13728
	v_exp_f32_e32 v48, v48
	v_add_f32_e32 v0, 1.0, v47
	v_fma_f32 v47, -v46, v46, 1.0
	v_rcp_f32_e32 v0, v0
	v_max_f32_e32 v47, 0, v47
	v_add_f32_e32 v48, 1.0, v48
	s_waitcnt lgkmcnt(1)
	v_add_f32_e32 v2, v2, v78
	v_sqrt_f32_e32 v47, v47
	v_rcp_f32_e32 v48, v48
	v_mul_f32_e32 v2, 0xbfb8aa3b, v2
	v_exp_f32_e32 v2, v2
	v_mul_f32_e32 v0, v95, v0
	v_add_f32_e32 v49, v65, v125
	v_mul_f32_e32 v49, 0xbfb8aa3b, v49
	v_mul_f32_e32 v47, v0, v47
	v_mul_f32_e32 v0, v129, v48
	v_exp_f32_e32 v49, v49
	v_exp_f32_e32 v48, v0
	ds_read_b128 v[114:117], v89 offset:13952
	ds_read_b128 v[118:121], v89 offset:14208
	v_add_f32_e32 v2, 1.0, v2
	v_add_f32_e32 v3, v3, v79
	v_rcp_f32_e32 v2, v2
	v_mul_f32_e32 v3, 0xbfb8aa3b, v3
	v_exp_f32_e32 v3, v3
	v_add_f32_e32 v0, 1.0, v49
	v_fma_f32 v49, -v48, v48, 1.0
	s_waitcnt lgkmcnt(1)
; __device__ __forceinline__ float sigm(float x) { return __builtin_amdgcn_rcpf(1.f + __expf(-x)); }
; #define LAS __attribute__((address_space(3)))
; template <int PASS>
; __device__ __forceinline__ void lru_unit(const LruPtrs& args, LAS unsigned char* lds, int chunk, int bl, int g, int ck) {
;     ...
; #pragma unroll
;         for (int q = 0; q < 8; ++q) {
;             const f32x4 br = *(const LAS f32x4*)(PRM + 5 * 64 + 8 * q + 4 * hi), bi = *(const LAS f32x4*)(PRM + 6 * 64 + 8 * q + 4 * hi), cf = *(const LAS f32x4*)(PRM + 7 * 64 + 8 * q + 4 * hi);
; #pragma unroll
;             for (int p = 0; p < 4; ++p) { const int rb = q >> 2, r = (q & 3) * 4 + p;
;                 const float rr = pg8::sigm(ar[rb][r] + br[p]), ii = pg8::sigm(ai_[rb][r] + bi[p]);
;                 const float a0 = __builtin_amdgcn_exp2f(cf[p] * rr);
;                 av[q][p] = a0; uv[q][p] = __builtin_amdgcn_sqrtf(fmaxf(1.f - a0 * a0, 0.f)) * (ii * xc[q][p]); }
	v_add_f32_e32 v18, v18, v114
	v_rcp_f32_e32 v0, v0
	v_max_f32_e32 v49, 0, v49
	v_mul_f32_e32 v18, 0xbfb8aa3b, v18
	s_waitcnt lgkmcnt(0)
	v_mul_f32_e32 v2, v118, v2
	v_sqrt_f32_e32 v49, v49
	v_exp_f32_e32 v18, v18
	v_exp_f32_e32 v62, v2
	v_add_f32_e32 v3, 1.0, v3
	v_rcp_f32_e32 v3, v3
	v_mul_f32_e32 v0, v90, v0
	v_mul_f32_e32 v49, v0, v49
	v_add_f32_e32 v0, 1.0, v18
	v_fma_f32 v2, -v62, v62, 1.0
	v_add_f32_e32 v18, v19, v115
	v_rcp_f32_e32 v0, v0
	v_max_f32_e32 v2, 0, v2
	v_mul_f32_e32 v18, 0xbfb8aa3b, v18
	v_mul_f32_e32 v3, v119, v3
	v_sqrt_f32_e32 v2, v2
	v_exp_f32_e32 v18, v18
	v_exp_f32_e32 v64, v3
	v_mul_f32_e32 v0, v91, v0
	v_mul_f32_e32 v63, v0, v2
	v_add_f32_e32 v0, 1.0, v18
	v_fma_f32 v2, -v64, v64, 1.0
	v_add_f32_e32 v3, v4, v80
	v_rcp_f32_e32 v0, v0
	v_mul_f32_e32 v3, 0xbfb8aa3b, v3
	v_max_f32_e32 v2, 0, v2
	v_exp_f32_e32 v3, v3
	v_sqrt_f32_e32 v4, v2
	v_mul_f32_e32 v0, v107, v0
	v_add_f32_e32 v6, v6, v110
	v_add_f32_e32 v2, 1.0, v3
	v_mul_f32_e32 v65, v0, v4
	v_add_f32_e32 v4, v5, v81
	v_rcp_f32_e32 v2, v2
	v_mul_f32_e32 v4, 0xbfb8aa3b, v4
	v_exp_f32_e32 v4, v4
	v_add_f32_e32 v3, v20, v116
	v_mul_f32_e32 v3, 0xbfb8aa3b, v3
	v_mul_f32_e32 v2, v120, v2
	v_exp_f32_e32 v3, v3
	v_exp_f32_e32 v2, v2
	v_add_f32_e32 v4, 1.0, v4
	v_rcp_f32_e32 v4, v4
	v_mul_f32_e32 v6, 0xbfb8aa3b, v6
	v_exp_f32_e32 v6, v6
	v_add_f32_e32 v0, 1.0, v3
	v_fma_f32 v3, -v2, v2, 1.0
	v_add_f32_e32 v5, v21, v117
	ds_read_b128 v[122:125], v89 offset:13984
	ds_read_b128 v[126:129], v89 offset:14240
	v_rcp_f32_e32 v0, v0
	v_max_f32_e32 v3, 0, v3
	v_mul_f32_e32 v5, 0xbfb8aa3b, v5
	v_mul_f32_e32 v4, v121, v4
	v_sqrt_f32_e32 v3, v3
	v_exp_f32_e32 v5, v5
	v_exp_f32_e32 v4, v4
	v_add_f32_e32 v6, 1.0, v6
	v_add_f32_e32 v7, v7, v111
	v_rcp_f32_e32 v6, v6
	v_mul_f32_e32 v7, 0xbfb8aa3b, v7
	v_exp_f32_e32 v7, v7
	v_mul_f32_e32 v0, v108, v0
	v_mul_f32_e32 v3, v0, v3
	v_add_f32_e32 v0, 1.0, v5
	v_fma_f32 v5, -v4, v4, 1.0
	s_waitcnt lgkmcnt(1)
	v_add_f32_e32 v18, v22, v122
	v_rcp_f32_e32 v0, v0
	v_max_f32_e32 v5, 0, v5
	v_mul_f32_e32 v18, 0xbfb8aa3b, v18
	s_waitcnt lgkmcnt(0)
	v_mul_f32_e32 v6, v126, v6
	v_sqrt_f32_e32 v5, v5
	v_exp_f32_e32 v19, v18
	v_exp_f32_e32 v18, v6
	v_add_f32_e32 v7, 1.0, v7
	v_rcp_f32_e32 v7, v7
	v_mul_f32_e32 v0, v105, v0
	v_mul_f32_e32 v5, v0, v5
	v_add_f32_e32 v0, 1.0, v19
	v_fma_f32 v6, -v18, v18, 1.0
	v_rcp_f32_e32 v0, v0
	v_max_f32_e32 v6, 0, v6
	v_add_f32_e32 v19, v23, v123
	v_mul_f32_e32 v7, v127, v7
	v_sqrt_f32_e32 v6, v6
	v_mul_f32_e32 v19, 0xbfb8aa3b, v19
	v_exp_f32_e32 v20, v7
	v_add_f32_e32 v7, v8, v112
	v_exp_f32_e32 v21, v19
	v_mul_f32_e32 v7, 0xbfb8aa3b, v7
	v_exp_f32_e32 v7, v7
	v_mul_f32_e32 v0, v104, v0
	v_mul_f32_e32 v19, v0, v6
	v_fma_f32 v6, -v20, v20, 1.0
	v_add_f32_e32 v0, 1.0, v21
	v_max_f32_e32 v6, 0, v6
	v_rcp_f32_e32 v0, v0
	v_sqrt_f32_e32 v8, v6
	v_add_f32_e32 v6, 1.0, v7
	v_add_f32_e32 v7, v24, v124
	v_rcp_f32_e32 v6, v6
	v_mul_f32_e32 v7, 0xbfb8aa3b, v7
	v_exp_f32_e32 v7, v7
	v_mul_f32_e32 v0, v101, v0
	v_mul_f32_e32 v6, v128, v6
	v_mul_f32_e32 v21, v0, v8
	v_add_f32_e32 v8, v9, v113
	v_exp_f32_e32 v6, v6
	v_add_f32_e32 v0, 1.0, v7
	v_mul_f32_e32 v8, 0xbfb8aa3b, v8
	ds_read_b128 v[78:81], v89 offset:13760
	v_rcp_f32_e32 v0, v0
	v_exp_f32_e32 v8, v8
	v_fma_f32 v7, -v6, v6, 1.0
	v_max_f32_e32 v7, 0, v7
	v_mul_f32_e32 v0, v98, v0
	v_add_f32_e32 v8, 1.0, v8
	ds_read_b128 v[96:99], v89 offset:13792
	s_waitcnt lgkmcnt(1)
	v_add_f32_e32 v10, v10, v78
	v_sqrt_f32_e32 v7, v7
	v_rcp_f32_e32 v8, v8
	v_mul_f32_e32 v10, 0xbfb8aa3b, v10
	v_exp_f32_e32 v10, v10
	v_add_f32_e32 v9, v25, v125
	v_mul_f32_e32 v9, 0xbfb8aa3b, v9
	v_mul_f32_e32 v7, v0, v7
	v_mul_f32_e32 v0, v129, v8
	v_exp_f32_e32 v9, v9
	v_exp_f32_e32 v8, v0
	ds_read_b128 v[100:103], v89 offset:14016
	ds_read_b128 v[104:107], v89 offset:14272
	v_add_f32_e32 v10, 1.0, v10
	v_add_f32_e32 v11, v11, v79
	v_rcp_f32_e32 v10, v10
	v_mul_f32_e32 v11, 0xbfb8aa3b, v11
	v_exp_f32_e32 v11, v11
	v_add_f32_e32 v0, 1.0, v9
	v_fma_f32 v9, -v8, v8, 1.0
	s_waitcnt lgkmcnt(1)
	v_add_f32_e32 v22, v26, v100
	v_rcp_f32_e32 v0, v0
	v_max_f32_e32 v9, 0, v9
	v_mul_f32_e32 v22, 0xbfb8aa3b, v22
	s_waitcnt lgkmcnt(0)
	v_mul_f32_e32 v10, v104, v10
	v_sqrt_f32_e32 v9, v9
	v_exp_f32_e32 v23, v22
	v_exp_f32_e32 v22, v10
	v_add_f32_e32 v11, 1.0, v11
	v_rcp_f32_e32 v11, v11
	v_mul_f32_e32 v0, v92, v0
	v_mul_f32_e32 v9, v0, v9
	v_add_f32_e32 v0, 1.0, v23
	v_fma_f32 v10, -v22, v22, 1.0
	v_add_f32_e32 v23, v27, v101
	v_rcp_f32_e32 v0, v0
	v_max_f32_e32 v10, 0, v10
	v_mul_f32_e32 v23, 0xbfb8aa3b, v23
	v_mul_f32_e32 v11, v105, v11
	v_sqrt_f32_e32 v10, v10
	v_exp_f32_e32 v25, v23
	v_exp_f32_e32 v24, v11
	v_mul_f32_e32 v0, v94, v0
	v_mul_f32_e32 v23, v0, v10
	v_add_f32_e32 v0, 1.0, v25
	v_fma_f32 v10, -v24, v24, 1.0
	v_add_f32_e32 v11, v12, v80
	v_rcp_f32_e32 v0, v0
	v_mul_f32_e32 v11, 0xbfb8aa3b, v11
	v_max_f32_e32 v10, 0, v10
	v_exp_f32_e32 v11, v11
	v_sqrt_f32_e32 v12, v10
	v_mul_f32_e32 v0, v93, v0
	v_add_f32_e32 v14, v14, v96
	v_add_f32_e32 v10, 1.0, v11
	v_mul_f32_e32 v25, v0, v12
	v_add_f32_e32 v12, v13, v81
	v_rcp_f32_e32 v10, v10
	v_mul_f32_e32 v12, 0xbfb8aa3b, v12
	v_exp_f32_e32 v12, v12
	v_add_f32_e32 v11, v28, v102
	v_mul_f32_e32 v11, 0xbfb8aa3b, v11
	v_mul_f32_e32 v10, v106, v10
	v_exp_f32_e32 v11, v11
	v_exp_f32_e32 v10, v10
	v_add_f32_e32 v12, 1.0, v12
	v_rcp_f32_e32 v12, v12
	v_mul_f32_e32 v14, 0xbfb8aa3b, v14
	v_exp_f32_e32 v14, v14
	v_add_f32_e32 v0, 1.0, v11
	v_fma_f32 v11, -v10, v10, 1.0
	v_add_f32_e32 v13, v29, v103
	ds_read_b128 v[108:111], v89 offset:14048
	ds_read_b128 v[112:115], v89 offset:14304
	v_rcp_f32_e32 v0, v0
	v_max_f32_e32 v11, 0, v11
	v_mul_f32_e32 v13, 0xbfb8aa3b, v13
	v_mul_f32_e32 v12, v107, v12
	v_sqrt_f32_e32 v11, v11
	v_exp_f32_e32 v13, v13
	v_exp_f32_e32 v12, v12
	v_add_f32_e32 v14, 1.0, v14
	v_rcp_f32_e32 v14, v14
	v_mul_f32_e32 v0, v83, v0
	v_mul_f32_e32 v11, v0, v11
	v_add_f32_e32 v0, 1.0, v13
	v_fma_f32 v13, -v12, v12, 1.0
	s_waitcnt lgkmcnt(1)
; #define GAS __attribute__((address_space(1)))
; template <int PASS>
; __device__ __forceinline__ void lru_unit(const LruPtrs& args, LAS unsigned char* lds, int chunk, int bl, int g, int ck) {
;     ...
; #pragma unroll
;         for (int q = 0; q < 8; ++q) {
;             const f32x4 br = *(const LAS f32x4*)(PRM + 5 * 64 + 8 * q + 4 * hi), bi = *(const LAS f32x4*)(PRM + 6 * 64 + 8 * q + 4 * hi), cf = *(const LAS f32x4*)(PRM + 7 * 64 + 8 * q + 4 * hi);
; #pragma unroll
;             for (int p = 0; p < 4; ++p) { const int rb = q >> 2, r = (q & 3) * 4 + p;
;                 const float rr = pg8::sigm(ar[rb][r] + br[p]), ii = pg8::sigm(ai_[rb][r] + bi[p]);
;                 const float a0 = __builtin_amdgcn_exp2f(cf[p] * rr);
;                 av[q][p] = a0; uv[q][p] = __builtin_amdgcn_sqrtf(fmaxf(1.f - a0 * a0, 0.f)) * (ii * xc[q][p]); }
;         }
;     } else {
; #pragma unroll
;         for (int i = 0; i < 4; ++i) { const int idx = lane + 64 * i, r = idx >> 3, ch = idx & 7;
;             gtile[i] = *(const GAS v4u*)(Z + ((size_t)bl * T + ck * 256 + w * 32 + r) * LDZ + ZC_GA + g * 64 + ch * 8); }
; #pragma unroll
;         for (int q = 0; q < 8; ++q) { const v4u st = stash[q * 64];
; #pragma unroll
;             for (int p = 0; p < 4; ++p) { av[q][p] = pg8::bf_lo(st[p]); uv[q][p] = pg8::bf_hi(st[p]); } }
;         if (w == 0) { const GAS unsigned* gs = (const GAS unsigned*)((GAS v4u*)(ws + WS_STASH) + ((size_t)((bl * 16 + g) * 32 + ck) * NWAVES) * 8 * 64);
; #pragma unroll
;             for (int ww = 0; ww < 8; ++ww) gagg[ww] = gs[(size_t)((ww * 8 + (lane >> 3)) * 64 + 31 + 32 * ((lane >> 2) & 1)) * 4 + (lane & 3)]; }
;     }
;     float pA = 1.f, pH = 0.f;
;     if (PASS == 3) { typedef float f32x2v __attribute__((ext_vector_type(2))); f32x2v ag[4];
; #pragma unroll
;         for (int j = 0; j < 4; ++j) { const int cc = 4 * w + j; ag[j] = (f32x2v){1.f, 0.f}; if (cc < ck) ag[j] = *(const GAS f32x2v*)(AGG + ((size_t)(bl * 32 + cc) * D + g * 64 + lane) * 2); }
; #pragma unroll
;         for (int j = 0; j < 4; ++j) { pH = ag[j].x * pH + ag[j].y; pA = pA * ag[j].x; } }
;     ...
;     if (PASS == 1) {
; #pragma unroll
;     for (int q = 0; q < 8; ++q)
;         asm volatile("s_nop 1\n\t"
;             LRU_STEP("row_shr:1 row_mask:0xf bank_mask:0xf") LRU_STEP("row_shr:2 row_mask:0xf bank_mask:0xf") LRU_STEP("row_shr:4 row_mask:0xf bank_mask:0xf")
	v_add_f32_e32 v26, v30, v108
	v_rcp_f32_e32 v0, v0
	v_max_f32_e32 v13, 0, v13
	v_mul_f32_e32 v26, 0xbfb8aa3b, v26
	s_waitcnt lgkmcnt(0)
	v_mul_f32_e32 v14, v112, v14
	v_add_f32_e32 v15, v15, v97
	v_sqrt_f32_e32 v13, v13
	v_exp_f32_e32 v27, v26
	v_exp_f32_e32 v26, v14
	v_mul_f32_e32 v15, 0xbfb8aa3b, v15
	v_exp_f32_e32 v15, v15
	v_mul_f32_e32 v0, v82, v0
	v_mul_f32_e32 v13, v0, v13
	v_add_f32_e32 v0, 1.0, v27
	v_fma_f32 v14, -v26, v26, 1.0
	v_rcp_f32_e32 v0, v0
	v_max_f32_e32 v14, 0, v14
	v_add_f32_e32 v27, v31, v109
	v_add_f32_e32 v15, 1.0, v15
	v_sqrt_f32_e32 v14, v14
	v_mul_f32_e32 v27, 0xbfb8aa3b, v27
	v_rcp_f32_e32 v15, v15
	v_exp_f32_e32 v28, v27
	v_mul_f32_e32 v0, v77, v0
	v_mul_f32_e32 v27, v0, v14
	v_mul_f32_e32 v14, v113, v15
	v_add_f32_e32 v0, 1.0, v28
	v_exp_f32_e32 v28, v14
	v_add_f32_e32 v14, v16, v98
	v_mul_f32_e32 v14, 0xbfb8aa3b, v14
	v_rcp_f32_e32 v0, v0
	v_fma_f32 v15, -v28, v28, 1.0
	v_exp_f32_e32 v14, v14
	v_max_f32_e32 v15, 0, v15
	v_sqrt_f32_e32 v15, v15
	v_mul_f32_e32 v0, v76, v0
	v_add_f32_e32 v14, 1.0, v14
	v_rcp_f32_e32 v14, v14
	v_mul_f32_e32 v29, v0, v15
	v_add_f32_e32 v15, v17, v99
	v_mul_f32_e32 v15, 0xbfb8aa3b, v15
	v_exp_f32_e32 v15, v15
	v_add_f32_e32 v16, v32, v110
	v_mul_f32_e32 v16, 0xbfb8aa3b, v16
	v_mul_f32_e32 v14, v114, v14
	v_exp_f32_e32 v16, v16
	v_exp_f32_e32 v14, v14
	v_add_f32_e32 v15, 1.0, v15
	v_rcp_f32_e32 v15, v15
	v_add_f32_e32 v0, 1.0, v16
	v_fma_f32 v16, -v14, v14, 1.0
	v_max_f32_e32 v17, 0, v16
	v_add_f32_e32 v16, v33, v111
	v_mul_f32_e32 v16, 0xbfb8aa3b, v16
	v_mul_f32_e32 v15, v115, v15
	v_exp_f32_e32 v30, v16
	v_exp_f32_e32 v16, v15
	v_rcp_f32_e32 v0, v0
	v_sqrt_f32_e32 v15, v17
	v_add_f32_e32 v17, 1.0, v30
	v_fma_f32 v30, -v16, v16, 1.0
	v_rcp_f32_e32 v17, v17
	v_max_f32_e32 v30, 0, v30
	v_sqrt_f32_e32 v30, v30
	v_mul_f32_e32 v0, v74, v0
	s_mov_b64 s[4:5], 0x29c00000
	v_mul_f32_e32 v15, v0, v15
	v_mul_f32_e32 v0, v75, v17
	v_lshl_add_u64 v[70:71], v[72:73], 0, s[4:5]
	v_mul_f32_e32 v17, v0, v30
	v_add_co_u32_e32 v72, vcc, s2, v72
	s_nop 1
	v_fmac_f32_dpp v67, v67, v66 row_shr:1 row_mask:0xf bank_mask:0xf
	v_fmac_f32_dpp v69, v69, v68 row_shr:1 row_mask:0xf bank_mask:0xf
	v_fmac_f32_dpp v35, v35, v34 row_shr:1 row_mask:0xf bank_mask:0xf
	v_fmac_f32_dpp v37, v37, v36 row_shr:1 row_mask:0xf bank_mask:0xf
	v_mul_f32_dpp v66, v66, v66 row_shr:1 row_mask:0xf bank_mask:0xf
	v_mul_f32_dpp v68, v68, v68 row_shr:1 row_mask:0xf bank_mask:0xf
	v_mul_f32_dpp v34, v34, v34 row_shr:1 row_mask:0xf bank_mask:0xf
	v_mul_f32_dpp v36, v36, v36 row_shr:1 row_mask:0xf bank_mask:0xf
	v_fmac_f32_dpp v67, v67, v66 row_shr:2 row_mask:0xf bank_mask:0xf
	v_fmac_f32_dpp v69, v69, v68 row_shr:2 row_mask:0xf bank_mask:0xf
	v_fmac_f32_dpp v35, v35, v34 row_shr:2 row_mask:0xf bank_mask:0xf
	v_fmac_f32_dpp v37, v37, v36 row_shr:2 row_mask:0xf bank_mask:0xf
	v_mul_f32_dpp v66, v66, v66 row_shr:2 row_mask:0xf bank_mask:0xf
	v_mul_f32_dpp v68, v68, v68 row_shr:2 row_mask:0xf bank_mask:0xf
	v_mul_f32_dpp v34, v34, v34 row_shr:2 row_mask:0xf bank_mask:0xf
	v_mul_f32_dpp v36, v36, v36 row_shr:2 row_mask:0xf bank_mask:0xf
	v_fmac_f32_dpp v67, v67, v66 row_shr:4 row_mask:0xf bank_mask:0xf
	v_fmac_f32_dpp v69, v69, v68 row_shr:4 row_mask:0xf bank_mask:0xf
	v_fmac_f32_dpp v35, v35, v34 row_shr:4 row_mask:0xf bank_mask:0xf
	v_fmac_f32_dpp v37, v37, v36 row_shr:4 row_mask:0xf bank_mask:0xf
	v_mul_f32_dpp v66, v66, v66 row_shr:4 row_mask:0xf bank_mask:0xf
	v_mul_f32_dpp v68, v68, v68 row_shr:4 row_mask:0xf bank_mask:0xf
	v_mul_f32_dpp v34, v34, v34 row_shr:4 row_mask:0xf bank_mask:0xf
	v_mul_f32_dpp v36, v36, v36 row_shr:4 row_mask:0xf bank_mask:0xf
	v_fmac_f32_dpp v67, v67, v66 row_shr:8 row_mask:0xf bank_mask:0xf
	v_fmac_f32_dpp v69, v69, v68 row_shr:8 row_mask:0xf bank_mask:0xf
	v_fmac_f32_dpp v35, v35, v34 row_shr:8 row_mask:0xf bank_mask:0xf
	v_fmac_f32_dpp v37, v37, v36 row_shr:8 row_mask:0xf bank_mask:0xf
	v_mul_f32_dpp v66, v66, v66 row_shr:8 row_mask:0xf bank_mask:0xf
	v_mul_f32_dpp v68, v68, v68 row_shr:8 row_mask:0xf bank_mask:0xf
	v_mul_f32_dpp v34, v34, v34 row_shr:8 row_mask:0xf bank_mask:0xf
	v_mul_f32_dpp v36, v36, v36 row_shr:8 row_mask:0xf bank_mask:0xf
	v_fmac_f32_dpp v67, v67, v66 row_bcast:15 row_mask:0xa bank_mask:0xf
	v_fmac_f32_dpp v69, v69, v68 row_bcast:15 row_mask:0xa bank_mask:0xf
	v_fmac_f32_dpp v35, v35, v34 row_bcast:15 row_mask:0xa bank_mask:0xf
	v_fmac_f32_dpp v37, v37, v36 row_bcast:15 row_mask:0xa bank_mask:0xf
	v_mul_f32_dpp v66, v66, v66 row_bcast:15 row_mask:0xa bank_mask:0xf
	v_mul_f32_dpp v68, v68, v68 row_bcast:15 row_mask:0xa bank_mask:0xf
	v_mul_f32_dpp v34, v34, v34 row_bcast:15 row_mask:0xa bank_mask:0xf
	v_mul_f32_dpp v36, v36, v36 row_bcast:15 row_mask:0xa bank_mask:0xf

; template <int PASS>
; __device__ __forceinline__ void lru_unit(const LruPtrs& args, LAS unsigned char* lds, int chunk, int bl, int g, int ck) {
;     ...
;     if (PASS == 1) {
; #pragma unroll
;     for (int q = 0; q < 8; ++q)
;         asm volatile("s_nop 1\n\t"
;             LRU_STEP("row_shr:1 row_mask:0xf bank_mask:0xf") LRU_STEP("row_shr:2 row_mask:0xf bank_mask:0xf") LRU_STEP("row_shr:4 row_mask:0xf bank_mask:0xf")
;             LRU_STEP("row_shr:8 row_mask:0xf bank_mask:0xf") LRU_STEP("row_bcast:15 row_mask:0xa bank_mask:0xf")
;             : "+v"(uv[q][0]), "+v"(av[q][0]), "+v"(uv[q][1]), "+v"(av[q][1]), "+v"(uv[q][2]), "+v"(av[q][2]), "+v"(uv[q][3]), "+v"(av[q][3]));
	s_nop 1
	v_fmac_f32_dpp v51, v51, v50 row_shr:1 row_mask:0xf bank_mask:0xf
	v_fmac_f32_dpp v53, v53, v52 row_shr:1 row_mask:0xf bank_mask:0xf
	v_fmac_f32_dpp v39, v39, v38 row_shr:1 row_mask:0xf bank_mask:0xf
	v_fmac_f32_dpp v41, v41, v40 row_shr:1 row_mask:0xf bank_mask:0xf
	v_mul_f32_dpp v50, v50, v50 row_shr:1 row_mask:0xf bank_mask:0xf
	v_mul_f32_dpp v52, v52, v52 row_shr:1 row_mask:0xf bank_mask:0xf
	v_mul_f32_dpp v38, v38, v38 row_shr:1 row_mask:0xf bank_mask:0xf
	v_mul_f32_dpp v40, v40, v40 row_shr:1 row_mask:0xf bank_mask:0xf
	v_fmac_f32_dpp v51, v51, v50 row_shr:2 row_mask:0xf bank_mask:0xf
	v_fmac_f32_dpp v53, v53, v52 row_shr:2 row_mask:0xf bank_mask:0xf
	v_fmac_f32_dpp v39, v39, v38 row_shr:2 row_mask:0xf bank_mask:0xf
	v_fmac_f32_dpp v41, v41, v40 row_shr:2 row_mask:0xf bank_mask:0xf
	v_mul_f32_dpp v50, v50, v50 row_shr:2 row_mask:0xf bank_mask:0xf
	v_mul_f32_dpp v52, v52, v52 row_shr:2 row_mask:0xf bank_mask:0xf
	v_mul_f32_dpp v38, v38, v38 row_shr:2 row_mask:0xf bank_mask:0xf
	v_mul_f32_dpp v40, v40, v40 row_shr:2 row_mask:0xf bank_mask:0xf
	v_fmac_f32_dpp v51, v51, v50 row_shr:4 row_mask:0xf bank_mask:0xf
	v_fmac_f32_dpp v53, v53, v52 row_shr:4 row_mask:0xf bank_mask:0xf
	v_fmac_f32_dpp v39, v39, v38 row_shr:4 row_mask:0xf bank_mask:0xf
	v_fmac_f32_dpp v41, v41, v40 row_shr:4 row_mask:0xf bank_mask:0xf
	v_mul_f32_dpp v50, v50, v50 row_shr:4 row_mask:0xf bank_mask:0xf
	v_mul_f32_dpp v52, v52, v52 row_shr:4 row_mask:0xf bank_mask:0xf
	v_mul_f32_dpp v38, v38, v38 row_shr:4 row_mask:0xf bank_mask:0xf
	v_mul_f32_dpp v40, v40, v40 row_shr:4 row_mask:0xf bank_mask:0xf
	v_fmac_f32_dpp v51, v51, v50 row_shr:8 row_mask:0xf bank_mask:0xf
	v_fmac_f32_dpp v53, v53, v52 row_shr:8 row_mask:0xf bank_mask:0xf
	v_fmac_f32_dpp v39, v39, v38 row_shr:8 row_mask:0xf bank_mask:0xf
	v_fmac_f32_dpp v41, v41, v40 row_shr:8 row_mask:0xf bank_mask:0xf
	v_mul_f32_dpp v50, v50, v50 row_shr:8 row_mask:0xf bank_mask:0xf
	v_mul_f32_dpp v52, v52, v52 row_shr:8 row_mask:0xf bank_mask:0xf
	v_mul_f32_dpp v38, v38, v38 row_shr:8 row_mask:0xf bank_mask:0xf
	v_mul_f32_dpp v40, v40, v40 row_shr:8 row_mask:0xf bank_mask:0xf
	v_fmac_f32_dpp v51, v51, v50 row_bcast:15 row_mask:0xa bank_mask:0xf
	v_fmac_f32_dpp v53, v53, v52 row_bcast:15 row_mask:0xa bank_mask:0xf
	v_fmac_f32_dpp v39, v39, v38 row_bcast:15 row_mask:0xa bank_mask:0xf
	v_fmac_f32_dpp v41, v41, v40 row_bcast:15 row_mask:0xa bank_mask:0xf
	v_mul_f32_dpp v50, v50, v50 row_bcast:15 row_mask:0xa bank_mask:0xf
	v_mul_f32_dpp v52, v52, v52 row_bcast:15 row_mask:0xa bank_mask:0xf
	v_mul_f32_dpp v38, v38, v38 row_bcast:15 row_mask:0xa bank_mask:0xf
	v_mul_f32_dpp v40, v40, v40 row_bcast:15 row_mask:0xa bank_mask:0xf

; template <int PASS>
; __device__ __forceinline__ void lru_unit(const LruPtrs& args, LAS unsigned char* lds, int chunk, int bl, int g, int ck) {
;     ...
;     if (PASS == 1) {
; #pragma unroll
;     for (int q = 0; q < 8; ++q)
;         asm volatile("s_nop 1\n\t"
;             LRU_STEP("row_shr:1 row_mask:0xf bank_mask:0xf") LRU_STEP("row_shr:2 row_mask:0xf bank_mask:0xf") LRU_STEP("row_shr:4 row_mask:0xf bank_mask:0xf")
;             LRU_STEP("row_shr:8 row_mask:0xf bank_mask:0xf") LRU_STEP("row_bcast:15 row_mask:0xa bank_mask:0xf")
;             : "+v"(uv[q][0]), "+v"(av[q][0]), "+v"(uv[q][1]), "+v"(av[q][1]), "+v"(uv[q][2]), "+v"(av[q][2]), "+v"(uv[q][3]), "+v"(av[q][3]));
	s_nop 1
	v_fmac_f32_dpp v55, v55, v54 row_shr:1 row_mask:0xf bank_mask:0xf
	v_fmac_f32_dpp v57, v57, v56 row_shr:1 row_mask:0xf bank_mask:0xf
	v_fmac_f32_dpp v43, v43, v42 row_shr:1 row_mask:0xf bank_mask:0xf
	v_fmac_f32_dpp v45, v45, v44 row_shr:1 row_mask:0xf bank_mask:0xf
	v_mul_f32_dpp v54, v54, v54 row_shr:1 row_mask:0xf bank_mask:0xf
	v_mul_f32_dpp v56, v56, v56 row_shr:1 row_mask:0xf bank_mask:0xf
	v_mul_f32_dpp v42, v42, v42 row_shr:1 row_mask:0xf bank_mask:0xf
	v_mul_f32_dpp v44, v44, v44 row_shr:1 row_mask:0xf bank_mask:0xf
	v_fmac_f32_dpp v55, v55, v54 row_shr:2 row_mask:0xf bank_mask:0xf
	v_fmac_f32_dpp v57, v57, v56 row_shr:2 row_mask:0xf bank_mask:0xf
	v_fmac_f32_dpp v43, v43, v42 row_shr:2 row_mask:0xf bank_mask:0xf
	v_fmac_f32_dpp v45, v45, v44 row_shr:2 row_mask:0xf bank_mask:0xf
	v_mul_f32_dpp v54, v54, v54 row_shr:2 row_mask:0xf bank_mask:0xf
	v_mul_f32_dpp v56, v56, v56 row_shr:2 row_mask:0xf bank_mask:0xf
	v_mul_f32_dpp v42, v42, v42 row_shr:2 row_mask:0xf bank_mask:0xf
	v_mul_f32_dpp v44, v44, v44 row_shr:2 row_mask:0xf bank_mask:0xf
	v_fmac_f32_dpp v55, v55, v54 row_shr:4 row_mask:0xf bank_mask:0xf
	v_fmac_f32_dpp v57, v57, v56 row_shr:4 row_mask:0xf bank_mask:0xf
	v_fmac_f32_dpp v43, v43, v42 row_shr:4 row_mask:0xf bank_mask:0xf
	v_fmac_f32_dpp v45, v45, v44 row_shr:4 row_mask:0xf bank_mask:0xf
	v_mul_f32_dpp v54, v54, v54 row_shr:4 row_mask:0xf bank_mask:0xf
	v_mul_f32_dpp v56, v56, v56 row_shr:4 row_mask:0xf bank_mask:0xf
	v_mul_f32_dpp v42, v42, v42 row_shr:4 row_mask:0xf bank_mask:0xf
	v_mul_f32_dpp v44, v44, v44 row_shr:4 row_mask:0xf bank_mask:0xf
	v_fmac_f32_dpp v55, v55, v54 row_shr:8 row_mask:0xf bank_mask:0xf
	v_fmac_f32_dpp v57, v57, v56 row_shr:8 row_mask:0xf bank_mask:0xf
	v_fmac_f32_dpp v43, v43, v42 row_shr:8 row_mask:0xf bank_mask:0xf
	v_fmac_f32_dpp v45, v45, v44 row_shr:8 row_mask:0xf bank_mask:0xf
	v_mul_f32_dpp v54, v54, v54 row_shr:8 row_mask:0xf bank_mask:0xf
	v_mul_f32_dpp v56, v56, v56 row_shr:8 row_mask:0xf bank_mask:0xf
	v_mul_f32_dpp v42, v42, v42 row_shr:8 row_mask:0xf bank_mask:0xf
	v_mul_f32_dpp v44, v44, v44 row_shr:8 row_mask:0xf bank_mask:0xf
	v_fmac_f32_dpp v55, v55, v54 row_bcast:15 row_mask:0xa bank_mask:0xf
	v_fmac_f32_dpp v57, v57, v56 row_bcast:15 row_mask:0xa bank_mask:0xf
	v_fmac_f32_dpp v43, v43, v42 row_bcast:15 row_mask:0xa bank_mask:0xf
	v_fmac_f32_dpp v45, v45, v44 row_bcast:15 row_mask:0xa bank_mask:0xf
	v_mul_f32_dpp v54, v54, v54 row_bcast:15 row_mask:0xa bank_mask:0xf
	v_mul_f32_dpp v56, v56, v56 row_bcast:15 row_mask:0xa bank_mask:0xf
	v_mul_f32_dpp v42, v42, v42 row_bcast:15 row_mask:0xa bank_mask:0xf
	v_mul_f32_dpp v44, v44, v44 row_bcast:15 row_mask:0xa bank_mask:0xf

; template <int PASS>
; __device__ __forceinline__ void lru_unit(const LruPtrs& args, LAS unsigned char* lds, int chunk, int bl, int g, int ck) {
;     ...
;     if (PASS == 1) {
; #pragma unroll
;     for (int q = 0; q < 8; ++q)
;         asm volatile("s_nop 1\n\t"
;             LRU_STEP("row_shr:1 row_mask:0xf bank_mask:0xf") LRU_STEP("row_shr:2 row_mask:0xf bank_mask:0xf") LRU_STEP("row_shr:4 row_mask:0xf bank_mask:0xf")
;             LRU_STEP("row_shr:8 row_mask:0xf bank_mask:0xf") LRU_STEP("row_bcast:15 row_mask:0xa bank_mask:0xf")
;             : "+v"(uv[q][0]), "+v"(av[q][0]), "+v"(uv[q][1]), "+v"(av[q][1]), "+v"(uv[q][2]), "+v"(av[q][2]), "+v"(uv[q][3]), "+v"(av[q][3]));
	s_nop 1
	v_fmac_f32_dpp v59, v59, v58 row_shr:1 row_mask:0xf bank_mask:0xf
	v_fmac_f32_dpp v61, v61, v60 row_shr:1 row_mask:0xf bank_mask:0xf
	v_fmac_f32_dpp v47, v47, v46 row_shr:1 row_mask:0xf bank_mask:0xf
	v_fmac_f32_dpp v49, v49, v48 row_shr:1 row_mask:0xf bank_mask:0xf
	v_mul_f32_dpp v58, v58, v58 row_shr:1 row_mask:0xf bank_mask:0xf
	v_mul_f32_dpp v60, v60, v60 row_shr:1 row_mask:0xf bank_mask:0xf
	v_mul_f32_dpp v46, v46, v46 row_shr:1 row_mask:0xf bank_mask:0xf
	v_mul_f32_dpp v48, v48, v48 row_shr:1 row_mask:0xf bank_mask:0xf
	v_fmac_f32_dpp v59, v59, v58 row_shr:2 row_mask:0xf bank_mask:0xf
	v_fmac_f32_dpp v61, v61, v60 row_shr:2 row_mask:0xf bank_mask:0xf
	v_fmac_f32_dpp v47, v47, v46 row_shr:2 row_mask:0xf bank_mask:0xf
	v_fmac_f32_dpp v49, v49, v48 row_shr:2 row_mask:0xf bank_mask:0xf
	v_mul_f32_dpp v58, v58, v58 row_shr:2 row_mask:0xf bank_mask:0xf
	v_mul_f32_dpp v60, v60, v60 row_shr:2 row_mask:0xf bank_mask:0xf
	v_mul_f32_dpp v46, v46, v46 row_shr:2 row_mask:0xf bank_mask:0xf
	v_mul_f32_dpp v48, v48, v48 row_shr:2 row_mask:0xf bank_mask:0xf
	v_fmac_f32_dpp v59, v59, v58 row_shr:4 row_mask:0xf bank_mask:0xf
	v_fmac_f32_dpp v61, v61, v60 row_shr:4 row_mask:0xf bank_mask:0xf
	v_fmac_f32_dpp v47, v47, v46 row_shr:4 row_mask:0xf bank_mask:0xf
	v_fmac_f32_dpp v49, v49, v48 row_shr:4 row_mask:0xf bank_mask:0xf
	v_mul_f32_dpp v58, v58, v58 row_shr:4 row_mask:0xf bank_mask:0xf
	v_mul_f32_dpp v60, v60, v60 row_shr:4 row_mask:0xf bank_mask:0xf
	v_mul_f32_dpp v46, v46, v46 row_shr:4 row_mask:0xf bank_mask:0xf
	v_mul_f32_dpp v48, v48, v48 row_shr:4 row_mask:0xf bank_mask:0xf
	v_fmac_f32_dpp v59, v59, v58 row_shr:8 row_mask:0xf bank_mask:0xf
	v_fmac_f32_dpp v61, v61, v60 row_shr:8 row_mask:0xf bank_mask:0xf
	v_fmac_f32_dpp v47, v47, v46 row_shr:8 row_mask:0xf bank_mask:0xf
	v_fmac_f32_dpp v49, v49, v48 row_shr:8 row_mask:0xf bank_mask:0xf
	v_mul_f32_dpp v58, v58, v58 row_shr:8 row_mask:0xf bank_mask:0xf
	v_mul_f32_dpp v60, v60, v60 row_shr:8 row_mask:0xf bank_mask:0xf
	v_mul_f32_dpp v46, v46, v46 row_shr:8 row_mask:0xf bank_mask:0xf
	v_mul_f32_dpp v48, v48, v48 row_shr:8 row_mask:0xf bank_mask:0xf
	v_fmac_f32_dpp v59, v59, v58 row_bcast:15 row_mask:0xa bank_mask:0xf
	v_fmac_f32_dpp v61, v61, v60 row_bcast:15 row_mask:0xa bank_mask:0xf
	v_fmac_f32_dpp v47, v47, v46 row_bcast:15 row_mask:0xa bank_mask:0xf
	v_fmac_f32_dpp v49, v49, v48 row_bcast:15 row_mask:0xa bank_mask:0xf
	v_mul_f32_dpp v58, v58, v58 row_bcast:15 row_mask:0xa bank_mask:0xf
	v_mul_f32_dpp v60, v60, v60 row_bcast:15 row_mask:0xa bank_mask:0xf
	v_mul_f32_dpp v46, v46, v46 row_bcast:15 row_mask:0xa bank_mask:0xf
	v_mul_f32_dpp v48, v48, v48 row_bcast:15 row_mask:0xa bank_mask:0xf

; template <int PASS>
; __device__ __forceinline__ void lru_unit(const LruPtrs& args, LAS unsigned char* lds, int chunk, int bl, int g, int ck) {
;     ...
;     if (PASS == 1) {
; #pragma unroll
;     for (int q = 0; q < 8; ++q)
;         asm volatile("s_nop 1\n\t"
;             LRU_STEP("row_shr:1 row_mask:0xf bank_mask:0xf") LRU_STEP("row_shr:2 row_mask:0xf bank_mask:0xf") LRU_STEP("row_shr:4 row_mask:0xf bank_mask:0xf")
;             LRU_STEP("row_shr:8 row_mask:0xf bank_mask:0xf") LRU_STEP("row_bcast:15 row_mask:0xa bank_mask:0xf")
;             : "+v"(uv[q][0]), "+v"(av[q][0]), "+v"(uv[q][1]), "+v"(av[q][1]), "+v"(uv[q][2]), "+v"(av[q][2]), "+v"(uv[q][3]), "+v"(av[q][3]));
	s_nop 1
	v_fmac_f32_dpp v63, v63, v62 row_shr:1 row_mask:0xf bank_mask:0xf
	v_fmac_f32_dpp v65, v65, v64 row_shr:1 row_mask:0xf bank_mask:0xf
	v_fmac_f32_dpp v3, v3, v2 row_shr:1 row_mask:0xf bank_mask:0xf
	v_fmac_f32_dpp v5, v5, v4 row_shr:1 row_mask:0xf bank_mask:0xf
	v_mul_f32_dpp v62, v62, v62 row_shr:1 row_mask:0xf bank_mask:0xf
	v_mul_f32_dpp v64, v64, v64 row_shr:1 row_mask:0xf bank_mask:0xf
	v_mul_f32_dpp v2, v2, v2 row_shr:1 row_mask:0xf bank_mask:0xf
	v_mul_f32_dpp v4, v4, v4 row_shr:1 row_mask:0xf bank_mask:0xf
	v_fmac_f32_dpp v63, v63, v62 row_shr:2 row_mask:0xf bank_mask:0xf
	v_fmac_f32_dpp v65, v65, v64 row_shr:2 row_mask:0xf bank_mask:0xf
	v_fmac_f32_dpp v3, v3, v2 row_shr:2 row_mask:0xf bank_mask:0xf
	v_fmac_f32_dpp v5, v5, v4 row_shr:2 row_mask:0xf bank_mask:0xf
	v_mul_f32_dpp v62, v62, v62 row_shr:2 row_mask:0xf bank_mask:0xf
	v_mul_f32_dpp v64, v64, v64 row_shr:2 row_mask:0xf bank_mask:0xf
	v_mul_f32_dpp v2, v2, v2 row_shr:2 row_mask:0xf bank_mask:0xf
	v_mul_f32_dpp v4, v4, v4 row_shr:2 row_mask:0xf bank_mask:0xf
	v_fmac_f32_dpp v63, v63, v62 row_shr:4 row_mask:0xf bank_mask:0xf
	v_fmac_f32_dpp v65, v65, v64 row_shr:4 row_mask:0xf bank_mask:0xf
	v_fmac_f32_dpp v3, v3, v2 row_shr:4 row_mask:0xf bank_mask:0xf
	v_fmac_f32_dpp v5, v5, v4 row_shr:4 row_mask:0xf bank_mask:0xf
	v_mul_f32_dpp v62, v62, v62 row_shr:4 row_mask:0xf bank_mask:0xf
	v_mul_f32_dpp v64, v64, v64 row_shr:4 row_mask:0xf bank_mask:0xf
	v_mul_f32_dpp v2, v2, v2 row_shr:4 row_mask:0xf bank_mask:0xf
	v_mul_f32_dpp v4, v4, v4 row_shr:4 row_mask:0xf bank_mask:0xf
	v_fmac_f32_dpp v63, v63, v62 row_shr:8 row_mask:0xf bank_mask:0xf
	v_fmac_f32_dpp v65, v65, v64 row_shr:8 row_mask:0xf bank_mask:0xf
	v_fmac_f32_dpp v3, v3, v2 row_shr:8 row_mask:0xf bank_mask:0xf
	v_fmac_f32_dpp v5, v5, v4 row_shr:8 row_mask:0xf bank_mask:0xf
	v_mul_f32_dpp v62, v62, v62 row_shr:8 row_mask:0xf bank_mask:0xf
	v_mul_f32_dpp v64, v64, v64 row_shr:8 row_mask:0xf bank_mask:0xf
	v_mul_f32_dpp v2, v2, v2 row_shr:8 row_mask:0xf bank_mask:0xf
	v_mul_f32_dpp v4, v4, v4 row_shr:8 row_mask:0xf bank_mask:0xf
	v_fmac_f32_dpp v63, v63, v62 row_bcast:15 row_mask:0xa bank_mask:0xf
	v_fmac_f32_dpp v65, v65, v64 row_bcast:15 row_mask:0xa bank_mask:0xf
	v_fmac_f32_dpp v3, v3, v2 row_bcast:15 row_mask:0xa bank_mask:0xf
	v_fmac_f32_dpp v5, v5, v4 row_bcast:15 row_mask:0xa bank_mask:0xf
	v_mul_f32_dpp v62, v62, v62 row_bcast:15 row_mask:0xa bank_mask:0xf
	v_mul_f32_dpp v64, v64, v64 row_bcast:15 row_mask:0xa bank_mask:0xf
	v_mul_f32_dpp v2, v2, v2 row_bcast:15 row_mask:0xa bank_mask:0xf
	v_mul_f32_dpp v4, v4, v4 row_bcast:15 row_mask:0xa bank_mask:0xf

; template <int PASS>
; __device__ __forceinline__ void lru_unit(const LruPtrs& args, LAS unsigned char* lds, int chunk, int bl, int g, int ck) {
;     ...
;     if (PASS == 1) {
; #pragma unroll
;     for (int q = 0; q < 8; ++q)
;         asm volatile("s_nop 1\n\t"
;             LRU_STEP("row_shr:1 row_mask:0xf bank_mask:0xf") LRU_STEP("row_shr:2 row_mask:0xf bank_mask:0xf") LRU_STEP("row_shr:4 row_mask:0xf bank_mask:0xf")
;             LRU_STEP("row_shr:8 row_mask:0xf bank_mask:0xf") LRU_STEP("row_bcast:15 row_mask:0xa bank_mask:0xf")
;             : "+v"(uv[q][0]), "+v"(av[q][0]), "+v"(uv[q][1]), "+v"(av[q][1]), "+v"(uv[q][2]), "+v"(av[q][2]), "+v"(uv[q][3]), "+v"(av[q][3]));
	s_nop 1
	v_fmac_f32_dpp v19, v19, v18 row_shr:1 row_mask:0xf bank_mask:0xf
	v_fmac_f32_dpp v21, v21, v20 row_shr:1 row_mask:0xf bank_mask:0xf
	v_fmac_f32_dpp v7, v7, v6 row_shr:1 row_mask:0xf bank_mask:0xf
	v_fmac_f32_dpp v9, v9, v8 row_shr:1 row_mask:0xf bank_mask:0xf
	v_mul_f32_dpp v18, v18, v18 row_shr:1 row_mask:0xf bank_mask:0xf
	v_mul_f32_dpp v20, v20, v20 row_shr:1 row_mask:0xf bank_mask:0xf
	v_mul_f32_dpp v6, v6, v6 row_shr:1 row_mask:0xf bank_mask:0xf
	v_mul_f32_dpp v8, v8, v8 row_shr:1 row_mask:0xf bank_mask:0xf
	v_fmac_f32_dpp v19, v19, v18 row_shr:2 row_mask:0xf bank_mask:0xf
	v_fmac_f32_dpp v21, v21, v20 row_shr:2 row_mask:0xf bank_mask:0xf
	v_fmac_f32_dpp v7, v7, v6 row_shr:2 row_mask:0xf bank_mask:0xf
	v_fmac_f32_dpp v9, v9, v8 row_shr:2 row_mask:0xf bank_mask:0xf
	v_mul_f32_dpp v18, v18, v18 row_shr:2 row_mask:0xf bank_mask:0xf
	v_mul_f32_dpp v20, v20, v20 row_shr:2 row_mask:0xf bank_mask:0xf
	v_mul_f32_dpp v6, v6, v6 row_shr:2 row_mask:0xf bank_mask:0xf
	v_mul_f32_dpp v8, v8, v8 row_shr:2 row_mask:0xf bank_mask:0xf
	v_fmac_f32_dpp v19, v19, v18 row_shr:4 row_mask:0xf bank_mask:0xf
	v_fmac_f32_dpp v21, v21, v20 row_shr:4 row_mask:0xf bank_mask:0xf
	v_fmac_f32_dpp v7, v7, v6 row_shr:4 row_mask:0xf bank_mask:0xf
	v_fmac_f32_dpp v9, v9, v8 row_shr:4 row_mask:0xf bank_mask:0xf
	v_mul_f32_dpp v18, v18, v18 row_shr:4 row_mask:0xf bank_mask:0xf
	v_mul_f32_dpp v20, v20, v20 row_shr:4 row_mask:0xf bank_mask:0xf
	v_mul_f32_dpp v6, v6, v6 row_shr:4 row_mask:0xf bank_mask:0xf
	v_mul_f32_dpp v8, v8, v8 row_shr:4 row_mask:0xf bank_mask:0xf
	v_fmac_f32_dpp v19, v19, v18 row_shr:8 row_mask:0xf bank_mask:0xf
	v_fmac_f32_dpp v21, v21, v20 row_shr:8 row_mask:0xf bank_mask:0xf
	v_fmac_f32_dpp v7, v7, v6 row_shr:8 row_mask:0xf bank_mask:0xf
	v_fmac_f32_dpp v9, v9, v8 row_shr:8 row_mask:0xf bank_mask:0xf
	v_mul_f32_dpp v18, v18, v18 row_shr:8 row_mask:0xf bank_mask:0xf
	v_mul_f32_dpp v20, v20, v20 row_shr:8 row_mask:0xf bank_mask:0xf
	v_mul_f32_dpp v6, v6, v6 row_shr:8 row_mask:0xf bank_mask:0xf
	v_mul_f32_dpp v8, v8, v8 row_shr:8 row_mask:0xf bank_mask:0xf
	v_fmac_f32_dpp v19, v19, v18 row_bcast:15 row_mask:0xa bank_mask:0xf
	v_fmac_f32_dpp v21, v21, v20 row_bcast:15 row_mask:0xa bank_mask:0xf
	v_fmac_f32_dpp v7, v7, v6 row_bcast:15 row_mask:0xa bank_mask:0xf
	v_fmac_f32_dpp v9, v9, v8 row_bcast:15 row_mask:0xa bank_mask:0xf
	v_mul_f32_dpp v18, v18, v18 row_bcast:15 row_mask:0xa bank_mask:0xf
	v_mul_f32_dpp v20, v20, v20 row_bcast:15 row_mask:0xa bank_mask:0xf
	v_mul_f32_dpp v6, v6, v6 row_bcast:15 row_mask:0xa bank_mask:0xf
	v_mul_f32_dpp v8, v8, v8 row_bcast:15 row_mask:0xa bank_mask:0xf

; template <int PASS>
; __device__ __forceinline__ void lru_unit(const LruPtrs& args, LAS unsigned char* lds, int chunk, int bl, int g, int ck) {
;     ...
;     if (PASS == 1) {
; #pragma unroll
;     for (int q = 0; q < 8; ++q)
;         asm volatile("s_nop 1\n\t"
;             LRU_STEP("row_shr:1 row_mask:0xf bank_mask:0xf") LRU_STEP("row_shr:2 row_mask:0xf bank_mask:0xf") LRU_STEP("row_shr:4 row_mask:0xf bank_mask:0xf")
;             LRU_STEP("row_shr:8 row_mask:0xf bank_mask:0xf") LRU_STEP("row_bcast:15 row_mask:0xa bank_mask:0xf")
;             : "+v"(uv[q][0]), "+v"(av[q][0]), "+v"(uv[q][1]), "+v"(av[q][1]), "+v"(uv[q][2]), "+v"(av[q][2]), "+v"(uv[q][3]), "+v"(av[q][3]));
	s_nop 1
	v_fmac_f32_dpp v23, v23, v22 row_shr:1 row_mask:0xf bank_mask:0xf
	v_fmac_f32_dpp v25, v25, v24 row_shr:1 row_mask:0xf bank_mask:0xf
	v_fmac_f32_dpp v11, v11, v10 row_shr:1 row_mask:0xf bank_mask:0xf
	v_fmac_f32_dpp v13, v13, v12 row_shr:1 row_mask:0xf bank_mask:0xf
	v_mul_f32_dpp v22, v22, v22 row_shr:1 row_mask:0xf bank_mask:0xf
	v_mul_f32_dpp v24, v24, v24 row_shr:1 row_mask:0xf bank_mask:0xf
	v_mul_f32_dpp v10, v10, v10 row_shr:1 row_mask:0xf bank_mask:0xf
	v_mul_f32_dpp v12, v12, v12 row_shr:1 row_mask:0xf bank_mask:0xf
	v_fmac_f32_dpp v23, v23, v22 row_shr:2 row_mask:0xf bank_mask:0xf
	v_fmac_f32_dpp v25, v25, v24 row_shr:2 row_mask:0xf bank_mask:0xf
	v_fmac_f32_dpp v11, v11, v10 row_shr:2 row_mask:0xf bank_mask:0xf
	v_fmac_f32_dpp v13, v13, v12 row_shr:2 row_mask:0xf bank_mask:0xf
	v_mul_f32_dpp v22, v22, v22 row_shr:2 row_mask:0xf bank_mask:0xf
	v_mul_f32_dpp v24, v24, v24 row_shr:2 row_mask:0xf bank_mask:0xf
	v_mul_f32_dpp v10, v10, v10 row_shr:2 row_mask:0xf bank_mask:0xf
	v_mul_f32_dpp v12, v12, v12 row_shr:2 row_mask:0xf bank_mask:0xf
	v_fmac_f32_dpp v23, v23, v22 row_shr:4 row_mask:0xf bank_mask:0xf
	v_fmac_f32_dpp v25, v25, v24 row_shr:4 row_mask:0xf bank_mask:0xf
	v_fmac_f32_dpp v11, v11, v10 row_shr:4 row_mask:0xf bank_mask:0xf
	v_fmac_f32_dpp v13, v13, v12 row_shr:4 row_mask:0xf bank_mask:0xf
	v_mul_f32_dpp v22, v22, v22 row_shr:4 row_mask:0xf bank_mask:0xf
	v_mul_f32_dpp v24, v24, v24 row_shr:4 row_mask:0xf bank_mask:0xf
	v_mul_f32_dpp v10, v10, v10 row_shr:4 row_mask:0xf bank_mask:0xf
	v_mul_f32_dpp v12, v12, v12 row_shr:4 row_mask:0xf bank_mask:0xf
	v_fmac_f32_dpp v23, v23, v22 row_shr:8 row_mask:0xf bank_mask:0xf
	v_fmac_f32_dpp v25, v25, v24 row_shr:8 row_mask:0xf bank_mask:0xf
	v_fmac_f32_dpp v11, v11, v10 row_shr:8 row_mask:0xf bank_mask:0xf
	v_fmac_f32_dpp v13, v13, v12 row_shr:8 row_mask:0xf bank_mask:0xf
	v_mul_f32_dpp v22, v22, v22 row_shr:8 row_mask:0xf bank_mask:0xf
	v_mul_f32_dpp v24, v24, v24 row_shr:8 row_mask:0xf bank_mask:0xf
	v_mul_f32_dpp v10, v10, v10 row_shr:8 row_mask:0xf bank_mask:0xf
	v_mul_f32_dpp v12, v12, v12 row_shr:8 row_mask:0xf bank_mask:0xf
	v_fmac_f32_dpp v23, v23, v22 row_bcast:15 row_mask:0xa bank_mask:0xf
	v_fmac_f32_dpp v25, v25, v24 row_bcast:15 row_mask:0xa bank_mask:0xf
	v_fmac_f32_dpp v11, v11, v10 row_bcast:15 row_mask:0xa bank_mask:0xf
	v_fmac_f32_dpp v13, v13, v12 row_bcast:15 row_mask:0xa bank_mask:0xf
	v_mul_f32_dpp v22, v22, v22 row_bcast:15 row_mask:0xa bank_mask:0xf
	v_mul_f32_dpp v24, v24, v24 row_bcast:15 row_mask:0xa bank_mask:0xf
	v_mul_f32_dpp v10, v10, v10 row_bcast:15 row_mask:0xa bank_mask:0xf
	v_mul_f32_dpp v12, v12, v12 row_bcast:15 row_mask:0xa bank_mask:0xf

; template <int PASS>
; __device__ __forceinline__ void lru_unit(const LruPtrs& args, LAS unsigned char* lds, int chunk, int bl, int g, int ck) {
;     ...
;     if (PASS == 1) {
; #pragma unroll
;     for (int q = 0; q < 8; ++q)
;         asm volatile("s_nop 1\n\t"
;             LRU_STEP("row_shr:1 row_mask:0xf bank_mask:0xf") LRU_STEP("row_shr:2 row_mask:0xf bank_mask:0xf") LRU_STEP("row_shr:4 row_mask:0xf bank_mask:0xf")
;             LRU_STEP("row_shr:8 row_mask:0xf bank_mask:0xf") LRU_STEP("row_bcast:15 row_mask:0xa bank_mask:0xf")
;             : "+v"(uv[q][0]), "+v"(av[q][0]), "+v"(uv[q][1]), "+v"(av[q][1]), "+v"(uv[q][2]), "+v"(av[q][2]), "+v"(uv[q][3]), "+v"(av[q][3]));
	s_nop 1
	v_fmac_f32_dpp v27, v27, v26 row_shr:1 row_mask:0xf bank_mask:0xf
	v_fmac_f32_dpp v29, v29, v28 row_shr:1 row_mask:0xf bank_mask:0xf
	v_fmac_f32_dpp v15, v15, v14 row_shr:1 row_mask:0xf bank_mask:0xf
	v_fmac_f32_dpp v17, v17, v16 row_shr:1 row_mask:0xf bank_mask:0xf
	v_mul_f32_dpp v26, v26, v26 row_shr:1 row_mask:0xf bank_mask:0xf
	v_mul_f32_dpp v28, v28, v28 row_shr:1 row_mask:0xf bank_mask:0xf
	v_mul_f32_dpp v14, v14, v14 row_shr:1 row_mask:0xf bank_mask:0xf
	v_mul_f32_dpp v16, v16, v16 row_shr:1 row_mask:0xf bank_mask:0xf
	v_fmac_f32_dpp v27, v27, v26 row_shr:2 row_mask:0xf bank_mask:0xf
	v_fmac_f32_dpp v29, v29, v28 row_shr:2 row_mask:0xf bank_mask:0xf
	v_fmac_f32_dpp v15, v15, v14 row_shr:2 row_mask:0xf bank_mask:0xf
	v_fmac_f32_dpp v17, v17, v16 row_shr:2 row_mask:0xf bank_mask:0xf
	v_mul_f32_dpp v26, v26, v26 row_shr:2 row_mask:0xf bank_mask:0xf
	v_mul_f32_dpp v28, v28, v28 row_shr:2 row_mask:0xf bank_mask:0xf
	v_mul_f32_dpp v14, v14, v14 row_shr:2 row_mask:0xf bank_mask:0xf
	v_mul_f32_dpp v16, v16, v16 row_shr:2 row_mask:0xf bank_mask:0xf
	v_fmac_f32_dpp v27, v27, v26 row_shr:4 row_mask:0xf bank_mask:0xf
	v_fmac_f32_dpp v29, v29, v28 row_shr:4 row_mask:0xf bank_mask:0xf
	v_fmac_f32_dpp v15, v15, v14 row_shr:4 row_mask:0xf bank_mask:0xf
	v_fmac_f32_dpp v17, v17, v16 row_shr:4 row_mask:0xf bank_mask:0xf
	v_mul_f32_dpp v26, v26, v26 row_shr:4 row_mask:0xf bank_mask:0xf
	v_mul_f32_dpp v28, v28, v28 row_shr:4 row_mask:0xf bank_mask:0xf
	v_mul_f32_dpp v14, v14, v14 row_shr:4 row_mask:0xf bank_mask:0xf
	v_mul_f32_dpp v16, v16, v16 row_shr:4 row_mask:0xf bank_mask:0xf
	v_fmac_f32_dpp v27, v27, v26 row_shr:8 row_mask:0xf bank_mask:0xf
	v_fmac_f32_dpp v29, v29, v28 row_shr:8 row_mask:0xf bank_mask:0xf
	v_fmac_f32_dpp v15, v15, v14 row_shr:8 row_mask:0xf bank_mask:0xf
	v_fmac_f32_dpp v17, v17, v16 row_shr:8 row_mask:0xf bank_mask:0xf
	v_mul_f32_dpp v26, v26, v26 row_shr:8 row_mask:0xf bank_mask:0xf
	v_mul_f32_dpp v28, v28, v28 row_shr:8 row_mask:0xf bank_mask:0xf
	v_mul_f32_dpp v14, v14, v14 row_shr:8 row_mask:0xf bank_mask:0xf
	v_mul_f32_dpp v16, v16, v16 row_shr:8 row_mask:0xf bank_mask:0xf
	v_fmac_f32_dpp v27, v27, v26 row_bcast:15 row_mask:0xa bank_mask:0xf
	v_fmac_f32_dpp v29, v29, v28 row_bcast:15 row_mask:0xa bank_mask:0xf
	v_fmac_f32_dpp v15, v15, v14 row_bcast:15 row_mask:0xa bank_mask:0xf
	v_fmac_f32_dpp v17, v17, v16 row_bcast:15 row_mask:0xa bank_mask:0xf
	v_mul_f32_dpp v26, v26, v26 row_bcast:15 row_mask:0xa bank_mask:0xf
	v_mul_f32_dpp v28, v28, v28 row_bcast:15 row_mask:0xa bank_mask:0xf
	v_mul_f32_dpp v14, v14, v14 row_bcast:15 row_mask:0xa bank_mask:0xf
	v_mul_f32_dpp v16, v16, v16 row_bcast:15 row_mask:0xa bank_mask:0xf

; __device__ __forceinline__ unsigned cvt_pk_bf16(float lo, float hi) { unsigned r; asm volatile("v_cvt_pk_bf16_f32 %0, %1, %2" : "=v"(r) : "v"(lo), "v"(hi)); return r; }
; template <int PASS>
; __device__ __forceinline__ void lru_unit(const LruPtrs& args, LAS unsigned char* lds, int chunk, int bl, int g, int ck) {
;     ...
; #pragma unroll
;     for (int q = 0; q < 8; ++q) { v4u st;
; #pragma unroll
;         for (int p = 0; p < 4; ++p) st[p] = pg8::cvt_pk_bf16(av[q][p], uv[q][p]);
;         stash[q * 64] = st; }
;     }
;     ...
;     if (PASS == 1 && n == 31) {
; #pragma unroll
;         for (int q = 0; q < 8; ++q)
; #pragma unroll
;             for (int p = 0; p < 4; ++p) { const int ci = 8 * q + 4 * hi + p; WAG[(w * 64 + ci) * 2] = av[q][p]; WAG[(w * 64 + ci) * 2 + 1] = uv[q][p]; }
;     }
	s_nop 0
	v_cvt_pk_bf16_f32 v30, v66, v67
	v_cvt_pk_bf16_f32 v31, v68, v69
	v_cvt_pk_bf16_f32 v32, v34, v35
	v_cvt_pk_bf16_f32 v33, v36, v37
	s_nop 0
	v_addc_co_u32_e32 v73, vcc, 0, v73, vcc
	global_store_dwordx4 v[72:73], v[30:33], off offset:-4096
	v_cmp_eq_u32_e32 vcc, 31, v87
	s_nop 0
	v_cvt_pk_bf16_f32 v30, v50, v51
	v_cvt_pk_bf16_f32 v31, v52, v53
	v_cvt_pk_bf16_f32 v32, v38, v39
	v_cvt_pk_bf16_f32 v33, v40, v41
	global_store_dwordx4 v[70:71], v[30:33], off offset:1024
	s_nop 1
	v_cvt_pk_bf16_f32 v30, v54, v55
	v_cvt_pk_bf16_f32 v31, v56, v57
	v_cvt_pk_bf16_f32 v32, v42, v43
	v_cvt_pk_bf16_f32 v33, v44, v45
	global_store_dwordx4 v[70:71], v[30:33], off offset:2048
	s_nop 1
	v_cvt_pk_bf16_f32 v30, v58, v59
	v_cvt_pk_bf16_f32 v31, v60, v61
	v_cvt_pk_bf16_f32 v32, v46, v47
	v_cvt_pk_bf16_f32 v33, v48, v49
	global_store_dwordx4 v[70:71], v[30:33], off offset:3072
	s_nop 1
	v_cvt_pk_bf16_f32 v30, v62, v63
	v_cvt_pk_bf16_f32 v31, v64, v65
	v_cvt_pk_bf16_f32 v32, v2, v3
	v_cvt_pk_bf16_f32 v33, v4, v5
	global_store_dwordx4 v[72:73], v[30:33], off
	s_nop 1
	v_cvt_pk_bf16_f32 v30, v18, v19
	v_cvt_pk_bf16_f32 v31, v20, v21
	v_cvt_pk_bf16_f32 v32, v6, v7
	v_cvt_pk_bf16_f32 v33, v8, v9
	global_store_dwordx4 v[72:73], v[30:33], off offset:1024
	s_nop 1
	v_cvt_pk_bf16_f32 v30, v22, v23
	v_cvt_pk_bf16_f32 v31, v24, v25
	v_cvt_pk_bf16_f32 v32, v10, v11
	v_cvt_pk_bf16_f32 v33, v12, v13
	global_store_dwordx4 v[72:73], v[30:33], off offset:2048
	s_nop 1
	v_cvt_pk_bf16_f32 v30, v26, v27
	v_cvt_pk_bf16_f32 v31, v28, v29
	v_cvt_pk_bf16_f32 v32, v14, v15
	v_cvt_pk_bf16_f32 v33, v16, v17
	global_store_dwordx4 v[72:73], v[30:33], off offset:3072
	s_and_saveexec_b64 s[4:5], vcc
	s_cbranch_execz .LBB0_447
	v_or_b32_e32 v0, s47, v88
	v_lshl_add_u32 v0, v0, 3, 0
	ds_write_b128 v0, v[66:69]
	ds_write_b128 v0, v[34:37] offset:16
	ds_write_b128 v0, v[50:53] offset:64
	ds_write_b128 v0, v[38:41] offset:80
	ds_write_b128 v0, v[54:57] offset:128
	ds_write_b128 v0, v[42:45] offset:144
	ds_write_b128 v0, v[58:61] offset:192
	ds_write_b128 v0, v[46:49] offset:208
	ds_write_b128 v0, v[62:65] offset:256
	ds_write_b128 v0, v[2:5] offset:272
	ds_write_b128 v0, v[18:21] offset:320
	ds_write_b128 v0, v[6:9] offset:336
	ds_write_b128 v0, v[22:25] offset:384
	ds_write_b128 v0, v[10:13] offset:400
	ds_write_b128 v0, v[26:29] offset:448
	ds_write_b128 v0, v[14:17] offset:464
